# ffn_act row loop: 2-deep row prefetch (two alternating load dest sets, x2 unroll, counted vmcnt(4)); FFN-up epilogue ss loads issued at tile start
# speedup vs baseline: 1.0045x; 1.0045x over previous
; template <class Epi, class Sched, bool ALIGN_EPI = false, bool SP2 = false>
; __device__ __forceinline__ void gemm_phase(PG8_LAS unsigned char* lds, const Gemm g, const Sched& S, const Epi& E) {
;     ...
;         const bool has_next = S.next(ui + 1, nxt);
;         const char* nA = has_next ? (const char*)g.A + (size_t)nxt.pm * tstep : cA; const char* nB = has_next ? (const char*)g.Bt + (size_t)nxt.pn * tstep : cB;
;         for (int t = 0; t < nt; t += 2) {
;             const bool last = (t == nt - 2);
;             const char* a1 = cA + (size_t)(t + 1) * kstep;
;             const char* a2 = last ? nA : cA + (size_t)(t + 2) * kstep; const char* b2 = last ? nB : cB + (size_t)(t + 2) * kstep;
;             const char* a3 = a2 + kstep; const char* b3 = b2 + kstep;
;             if (last && has_next) S.a_ready(nxt);
;             if constexpr (SP2) {
;             PG8_LDB(B0, 0, 0); PG8_LDB(B1, 0, 1); PG8_SCHED; PG8_LDA(At, 0, 0); PG8_STAGE(PG8_SA(1, 1), a1 + hstep, voffA);
;             PG8_WAIT_V(8); PG8_WAIT_L(0); PG8_BAR; PG8_MMA(0, 0, At, B0); PG8_MMA(0, 1, At, B1); PG8_BAR; PG8_SCHED;
;             PG8_LDA(At, 0, 1); PG8_STAGE(PG8_SB(0, 0), b2, voffB); PG8_STAGE(PG8_SB(0, 1), b2 + hstep, voffB); PG8_STAGE(PG8_SA(0, 0), a2, voffA);
;             PG8_WAIT_V(8); PG8_WAIT_L(0); PG8_BAR; PG8_MMA(1, 0, At, B0); PG8_MMA(1, 1, At, B1); PG8_BAR; PG8_SCHED;
;             PG8_LDB(B0, 1, 0); PG8_LDB(B1, 1, 1); PG8_SCHED; PG8_LDA(At, 1, 0); PG8_STAGE(PG8_SA(0, 1), a2 + hstep, voffA);
;             PG8_WAIT_V(8); PG8_WAIT_L(0); PG8_BAR; PG8_MMA(0, 0, At, B0); PG8_MMA(0, 1, At, B1); PG8_BAR; PG8_SCHED;
;             PG8_LDA(At, 1, 1); PG8_STAGE(PG8_SB(1, 0), b3, voffB); PG8_STAGE(PG8_SB(1, 1), b3 + hstep, voffB); PG8_STAGE(PG8_SA(1, 0), a3, voffA);
;             PG8_WAIT_V(8); PG8_WAIT_L(0); PG8_BAR; PG8_MMA(1, 0, At, B0); PG8_MMA(1, 1, At, B1); PG8_BAR; PG8_SCHED;
;             } else {
;             PG8_LDB(B0, 0, 0); PG8_SCHED; PG8_LDA(At, 0, 0); PG8_STAGE(PG8_SA(1, 1), a1 + hstep, voffA);
;             PG8_WAIT_L(8); PG8_BAR; PG8_WAIT_L(0); PG8_MMA(0, 0, At, B0); PG8_BAR; PG8_SCHED;
;             PG8_LDB(B1, 0, 1); PG8_STAGE(PG8_SB(0, 0), b2, voffB);
;             PG8_BAR; PG8_WAIT_L(0); PG8_MMA(0, 1, At, B1); PG8_BAR;
;             PG8_LDA(At, 0, 1); PG8_STAGE(PG8_SA(0, 0), a2, voffA);
;             PG8_BAR; PG8_WAIT_L(0); PG8_MMA(1, 0, At, B0); PG8_BAR; PG8_SCHED;
.LBB0_738:
	s_ashr_i32 s21, s20, 31
	s_lshl_b64 s[24:25], s[20:21], 19
	s_add_u32 s24, s46, s24
	s_addc_u32 s25, s47, s25
	s_and_b64 s[36:37], s[26:27], exec
	s_cselect_b32 s5, s25, s39
	s_cselect_b32 s9, s24, s38
	s_ashr_i32 s23, s22, 31
	s_lshl_b64 s[36:37], s[22:23], 19
	s_add_u32 s36, s49, s36
	s_addc_u32 s37, s50, s37
	s_and_b64 s[42:43], s[26:27], exec
	s_cselect_b32 s21, s37, s41
	s_cselect_b32 s23, s36, s40
	s_add_u32 s38, s38, 0x40080
	s_addc_u32 s39, s39, 0
	s_add_u32 s69, s40, 0x100
	v_mov_b32_e32 v0, 0
	s_addc_u32 s72, s41, 0
	s_mov_b32 s73, -2
	v_mov_b32_e32 v1, v0
	v_mov_b32_e32 v2, v0
	v_mov_b32_e32 v3, v0
	v_mov_b32_e32 v4, v0
	v_mov_b32_e32 v5, v0
	v_mov_b32_e32 v6, v0
	v_mov_b32_e32 v7, v0
	v_mov_b32_e32 v16, v0
	v_mov_b32_e32 v17, v0
	v_mov_b32_e32 v18, v0
	v_mov_b32_e32 v19, v0
	v_mov_b32_e32 v20, v0
	v_mov_b32_e32 v21, v0
	v_mov_b32_e32 v22, v0
	v_mov_b32_e32 v23, v0
	v_mov_b32_e32 v32, v0
	v_mov_b32_e32 v33, v0
	v_mov_b32_e32 v34, v0
	v_mov_b32_e32 v35, v0
	v_mov_b32_e32 v36, v0
	v_mov_b32_e32 v37, v0
	v_mov_b32_e32 v38, v0
	v_mov_b32_e32 v39, v0
	v_mov_b32_e32 v48, v0
	v_mov_b32_e32 v49, v0
	v_mov_b32_e32 v50, v0
	v_mov_b32_e32 v51, v0
	v_mov_b32_e32 v52, v0
	v_mov_b32_e32 v53, v0
	v_mov_b32_e32 v54, v0
	v_mov_b32_e32 v55, v0
	v_mov_b32_e32 v8, v0
	v_mov_b32_e32 v9, v0
	v_mov_b32_e32 v10, v0
	v_mov_b32_e32 v11, v0
	v_mov_b32_e32 v12, v0
	v_mov_b32_e32 v13, v0
	v_mov_b32_e32 v14, v0
	v_mov_b32_e32 v15, v0
	v_mov_b32_e32 v24, v0
	v_mov_b32_e32 v25, v0
	v_mov_b32_e32 v26, v0
	v_mov_b32_e32 v27, v0
	v_mov_b32_e32 v28, v0
	v_mov_b32_e32 v29, v0
	v_mov_b32_e32 v30, v0
	v_mov_b32_e32 v31, v0
	v_mov_b32_e32 v40, v0
	v_mov_b32_e32 v41, v0
	v_mov_b32_e32 v42, v0
	v_mov_b32_e32 v43, v0
	v_mov_b32_e32 v44, v0
	v_mov_b32_e32 v45, v0
	v_mov_b32_e32 v46, v0
	v_mov_b32_e32 v47, v0
	v_mov_b32_e32 v56, v0
	v_mov_b32_e32 v57, v0
	v_mov_b32_e32 v58, v0
	v_mov_b32_e32 v59, v0
	v_mov_b32_e32 v60, v0
	v_mov_b32_e32 v61, v0
	v_mov_b32_e32 v62, v0
	v_mov_b32_e32 v63, v0
	v_mov_b32_e32 v64, v0
	v_mov_b32_e32 v65, v0
	v_mov_b32_e32 v66, v0
	v_mov_b32_e32 v67, v0
	v_mov_b32_e32 v68, v0
	v_mov_b32_e32 v69, v0
	v_mov_b32_e32 v70, v0
	v_mov_b32_e32 v71, v0
	v_mov_b32_e32 v80, v0
	v_mov_b32_e32 v81, v0
	v_mov_b32_e32 v82, v0
	v_mov_b32_e32 v83, v0
	v_mov_b32_e32 v84, v0
	v_mov_b32_e32 v85, v0
	v_mov_b32_e32 v86, v0
	v_mov_b32_e32 v87, v0
	v_mov_b32_e32 v96, v0
	v_mov_b32_e32 v97, v0
	v_mov_b32_e32 v98, v0
	v_mov_b32_e32 v99, v0
	v_mov_b32_e32 v100, v0
	v_mov_b32_e32 v101, v0
	v_mov_b32_e32 v102, v0
	v_mov_b32_e32 v103, v0
	v_mov_b32_e32 v112, v0
	v_mov_b32_e32 v113, v0
	v_mov_b32_e32 v114, v0
	v_mov_b32_e32 v115, v0
	v_mov_b32_e32 v116, v0
	v_mov_b32_e32 v117, v0
	v_mov_b32_e32 v118, v0
	v_mov_b32_e32 v119, v0
	v_mov_b32_e32 v72, v0
	v_mov_b32_e32 v73, v0
	v_mov_b32_e32 v74, v0
	v_mov_b32_e32 v75, v0
	v_mov_b32_e32 v76, v0
	v_mov_b32_e32 v77, v0
	v_mov_b32_e32 v78, v0
	v_mov_b32_e32 v79, v0
	v_mov_b32_e32 v88, v0
	v_mov_b32_e32 v89, v0
	v_mov_b32_e32 v90, v0
	v_mov_b32_e32 v91, v0
	v_mov_b32_e32 v92, v0
	v_mov_b32_e32 v93, v0
	v_mov_b32_e32 v94, v0
	v_mov_b32_e32 v95, v0
	v_mov_b32_e32 v104, v0
	v_mov_b32_e32 v105, v0
	v_mov_b32_e32 v106, v0
	v_mov_b32_e32 v107, v0
	v_mov_b32_e32 v108, v0
	v_mov_b32_e32 v109, v0
	v_mov_b32_e32 v110, v0
	v_mov_b32_e32 v111, v0
	v_mov_b32_e32 v120, v0
	v_mov_b32_e32 v121, v0
	v_mov_b32_e32 v122, v0
	v_mov_b32_e32 v123, v0
	v_mov_b32_e32 v124, v0
	v_mov_b32_e32 v125, v0
	v_mov_b32_e32 v126, v0
	v_mov_b32_e32 v127, v0
	v_lshl_add_u32 v238, s8, 8, v140
	v_ashrrev_i32_e32 v239, 31, v238
	v_lshl_add_u64 v[238:239], v[238:239], 2, s[12:13]
	global_load_dword v240, v[238:239], off
	global_load_dword v241, v[238:239], off offset:64
	global_load_dword v242, v[238:239], off offset:128
	global_load_dword v243, v[238:239], off offset:192
	global_load_dword v244, v[238:239], off offset:512
	global_load_dword v245, v[238:239], off offset:576
	global_load_dword v246, v[238:239], off offset:640
	global_load_dword v247, v[238:239], off offset:704

; DI unsigned cvtpk(float lo, float hi) { f32x2 v = {lo, hi}; bfv2 r = __builtin_convertvector(v, bfv2); return __builtin_bit_cast(unsigned, r); }
;     DI void operator()(const f32x4 (&acc)[2][2][4][2], const Unit& u, int wr, int wc, int fr, int fq) const {
; #pragma unroll
;         for (int ai = 0; ai < 2; ++ai)
; #pragma unroll
;             for (int m = 0; m < 4; ++m) {
;                 const int r = u.pm * BM + ai * HALF + wr * 64 + m * 16 + fr;
; #pragma unroll
;                 for (int bj = 0; bj < 2; ++bj) f(r, u.pn * BM + bj * HALF + wc * 32 + 8 * fq, acc[ai][bj][m][0], acc[ai][bj][m][1]);
;                 asm volatile("" ::: "memory");
;             }
;     }
; DI void st_bf8(bf16_t* p, f32x4 a, f32x4 b) { u32x4 o = {cvtpk(a[0], a[1]), cvtpk(a[2], a[3]), cvtpk(b[0], b[1]), cvtpk(b[2], b[3])}; *(u32x4*)p = o; }
.LBB0_742:
	v_lshl_add_u32 v134, s8, 8, v140
	v_lshl_or_b32 v132, s4, 8, v142
	v_ashrrev_i32_e32 v135, 31, v134
	v_mad_i64_i32 v[136:137], s[4:5], v134, s65, 0
	v_cmp_gt_i32_e32 vcc, s66, v132
	v_lshl_add_u64 v[136:137], s[10:11], 0, v[136:137]
	v_ashrrev_i32_e32 v133, 31, v132
	v_lshl_add_u64 v[138:139], v[134:135], 2, s[12:13]
	s_and_saveexec_b64 s[8:9], vcc
	s_cbranch_execz .LBB0_744
	v_mov_b32_e32 v135, v240
	v_lshl_add_u64 v[148:149], v[132:133], 1, v[136:137]
	v_fmamk_f32 v135, v135, 0x3a800000, v146
	v_mul_f32_e32 v147, 0x4b800000, v135
	v_cmp_gt_f32_e64 s[4:5], s67, v135
	s_nop 1
	v_cndmask_b32_e64 v135, v135, v147, s[4:5]
	v_rsq_f32_e32 v135, v135
	s_nop 0
	v_mul_f32_e32 v147, 0x45800000, v135
	v_cndmask_b32_e64 v150, v135, v147, s[4:5]
	v_pk_mul_f32 v[126:127], v[126:127], v[150:151] op_sel_hi:[1,0]
	v_pk_mul_f32 v[124:125], v[124:125], v[150:151] op_sel_hi:[1,0]
	v_pk_mul_f32 v[152:153], v[122:123], v[150:151] op_sel_hi:[1,0]
	v_pk_mul_f32 v[122:123], v[120:121], v[150:151] op_sel_hi:[1,0]
	v_cvt_pk_bf16_f32 v120, v124, v125
	v_cvt_pk_bf16_f32 v121, v126, v127
	v_cvt_pk_bf16_f32 v122, v122, v123
	v_cvt_pk_bf16_f32 v123, v152, v153
	global_store_dwordx4 v[148:149], v[120:123], off
.LBB0_744:
	s_or_b64 exec, exec, s[8:9]
	s_nop 0
	v_or_b32_e32 v120, 0x80, v132
	v_cmp_gt_i32_e64 s[4:5], s66, v120
	s_and_saveexec_b64 s[38:39], s[4:5]
	s_cbranch_execz .LBB0_746
	v_mov_b32_e32 v120, v240
	v_fmamk_f32 v120, v120, 0x3a800000, v146
	v_mul_f32_e32 v121, 0x4b800000, v120
	v_cmp_gt_f32_e64 s[8:9], s67, v120
	s_nop 1
	v_cndmask_b32_e64 v120, v120, v121, s[8:9]
	v_rsq_f32_e32 v122, v120
	v_lshl_add_u64 v[120:121], v[132:133], 1, v[136:137]
	v_mul_f32_e32 v123, 0x45800000, v122
	v_cndmask_b32_e64 v122, v122, v123, s[8:9]
	v_pk_mul_f32 v[118:119], v[118:119], v[122:123] op_sel_hi:[1,0]
	v_pk_mul_f32 v[116:117], v[116:117], v[122:123] op_sel_hi:[1,0]
	v_pk_mul_f32 v[124:125], v[114:115], v[122:123] op_sel_hi:[1,0]
	v_pk_mul_f32 v[114:115], v[112:113], v[122:123] op_sel_hi:[1,0]
	v_cvt_pk_bf16_f32 v112, v116, v117
	v_cvt_pk_bf16_f32 v113, v118, v119
	v_cvt_pk_bf16_f32 v114, v114, v115
	v_cvt_pk_bf16_f32 v115, v124, v125
	global_store_dwordx4 v[120:121], v[112:115], off offset:256
.LBB0_746:
	s_or_b64 exec, exec, s[38:39]
	s_nop 0
	v_or_b32_e32 v114, 16, v134
	v_ashrrev_i32_e32 v115, 31, v114
	v_mad_i64_i32 v[112:113], s[8:9], v114, s65, 0
	v_lshl_add_u64 v[112:113], s[10:11], 0, v[112:113]
	v_lshl_add_u64 v[114:115], v[114:115], 2, s[12:13]
	s_and_saveexec_b64 s[38:39], vcc
	s_cbranch_execz .LBB0_748
	v_mov_b32_e32 v116, v241
	v_fmamk_f32 v116, v116, 0x3a800000, v146
	v_mul_f32_e32 v117, 0x4b800000, v116
	v_cmp_gt_f32_e64 s[8:9], s67, v116
	s_nop 1
	v_cndmask_b32_e64 v116, v116, v117, s[8:9]
	v_rsq_f32_e32 v118, v116
	v_lshl_add_u64 v[116:117], v[132:133], 1, v[112:113]
	v_mul_f32_e32 v119, 0x45800000, v118
	v_cndmask_b32_e64 v118, v118, v119, s[8:9]
	v_pk_mul_f32 v[110:111], v[110:111], v[118:119] op_sel_hi:[1,0]
	v_pk_mul_f32 v[108:109], v[108:109], v[118:119] op_sel_hi:[1,0]
	v_pk_mul_f32 v[120:121], v[106:107], v[118:119] op_sel_hi:[1,0]
	v_pk_mul_f32 v[106:107], v[104:105], v[118:119] op_sel_hi:[1,0]
	v_cvt_pk_bf16_f32 v104, v108, v109
	v_cvt_pk_bf16_f32 v105, v110, v111
	v_cvt_pk_bf16_f32 v106, v106, v107
	v_cvt_pk_bf16_f32 v107, v120, v121
	global_store_dwordx4 v[116:117], v[104:107], off
.LBB0_748:
	s_or_b64 exec, exec, s[38:39]
	s_and_saveexec_b64 s[38:39], s[4:5]
	s_cbranch_execz .LBB0_750
	v_mov_b32_e32 v104, v241
	v_fmamk_f32 v104, v104, 0x3a800000, v146
	v_mul_f32_e32 v105, 0x4b800000, v104
	v_cmp_gt_f32_e64 s[8:9], s67, v104
	s_nop 1
	v_cndmask_b32_e64 v104, v104, v105, s[8:9]
	v_rsq_f32_e32 v106, v104
	v_lshl_add_u64 v[104:105], v[132:133], 1, v[112:113]
	v_mul_f32_e32 v107, 0x45800000, v106
	v_cndmask_b32_e64 v106, v106, v107, s[8:9]
	v_pk_mul_f32 v[102:103], v[102:103], v[106:107] op_sel_hi:[1,0]
	v_pk_mul_f32 v[100:101], v[100:101], v[106:107] op_sel_hi:[1,0]
	v_pk_mul_f32 v[108:109], v[98:99], v[106:107] op_sel_hi:[1,0]
	v_pk_mul_f32 v[98:99], v[96:97], v[106:107] op_sel_hi:[1,0]
	v_cvt_pk_bf16_f32 v96, v100, v101
	v_cvt_pk_bf16_f32 v97, v102, v103
	v_cvt_pk_bf16_f32 v98, v98, v99
	v_cvt_pk_bf16_f32 v99, v108, v109
	global_store_dwordx4 v[104:105], v[96:99], off offset:256
.LBB0_750:
	s_or_b64 exec, exec, s[38:39]
	s_nop 0
	v_or_b32_e32 v98, 32, v134
	v_ashrrev_i32_e32 v99, 31, v98
	v_mad_i64_i32 v[96:97], s[8:9], v98, s65, 0
	v_lshl_add_u64 v[96:97], s[10:11], 0, v[96:97]
	v_lshl_add_u64 v[98:99], v[98:99], 2, s[12:13]
	s_and_saveexec_b64 s[38:39], vcc
	s_cbranch_execz .LBB0_752
	v_mov_b32_e32 v100, v242
	v_fmamk_f32 v100, v100, 0x3a800000, v146
	v_mul_f32_e32 v101, 0x4b800000, v100
	v_cmp_gt_f32_e64 s[8:9], s67, v100
	s_nop 1
	v_cndmask_b32_e64 v100, v100, v101, s[8:9]
	v_rsq_f32_e32 v102, v100
	v_lshl_add_u64 v[100:101], v[132:133], 1, v[96:97]
	v_mul_f32_e32 v103, 0x45800000, v102
	v_cndmask_b32_e64 v102, v102, v103, s[8:9]
	v_pk_mul_f32 v[94:95], v[94:95], v[102:103] op_sel_hi:[1,0]
	v_pk_mul_f32 v[92:93], v[92:93], v[102:103] op_sel_hi:[1,0]
	v_pk_mul_f32 v[104:105], v[90:91], v[102:103] op_sel_hi:[1,0]
	v_pk_mul_f32 v[90:91], v[88:89], v[102:103] op_sel_hi:[1,0]
	v_cvt_pk_bf16_f32 v88, v92, v93
	v_cvt_pk_bf16_f32 v89, v94, v95
	v_cvt_pk_bf16_f32 v90, v90, v91
	v_cvt_pk_bf16_f32 v91, v104, v105
	global_store_dwordx4 v[100:101], v[88:91], off
; DI unsigned cvtpk(float lo, float hi) { f32x2 v = {lo, hi}; bfv2 r = __builtin_convertvector(v, bfv2); return __builtin_bit_cast(unsigned, r); }
;     DI void operator()(const f32x4 (&acc)[2][2][4][2], const Unit& u, int wr, int wc, int fr, int fq) const {
; #pragma unroll
;         for (int ai = 0; ai < 2; ++ai)
; #pragma unroll
;             for (int m = 0; m < 4; ++m) {
;                 const int r = u.pm * BM + ai * HALF + wr * 64 + m * 16 + fr;
; #pragma unroll
;                 for (int bj = 0; bj < 2; ++bj) f(r, u.pn * BM + bj * HALF + wc * 32 + 8 * fq, acc[ai][bj][m][0], acc[ai][bj][m][1]);
;                 asm volatile("" ::: "memory");
;             }
;     }
; DI void st_bf8(bf16_t* p, f32x4 a, f32x4 b) { u32x4 o = {cvtpk(a[0], a[1]), cvtpk(a[2], a[3]), cvtpk(b[0], b[1]), cvtpk(b[2], b[3])}; *(u32x4*)p = o; }
.LBB0_752:
	s_or_b64 exec, exec, s[38:39]
	s_and_saveexec_b64 s[38:39], s[4:5]
	s_cbranch_execz .LBB0_754
	v_mov_b32_e32 v88, v242
	v_fmamk_f32 v88, v88, 0x3a800000, v146
	v_mul_f32_e32 v89, 0x4b800000, v88
	v_cmp_gt_f32_e64 s[8:9], s67, v88
	s_nop 1
	v_cndmask_b32_e64 v88, v88, v89, s[8:9]
	v_rsq_f32_e32 v90, v88
	v_lshl_add_u64 v[88:89], v[132:133], 1, v[96:97]
	v_mul_f32_e32 v91, 0x45800000, v90
	v_cndmask_b32_e64 v90, v90, v91, s[8:9]
	v_pk_mul_f32 v[86:87], v[86:87], v[90:91] op_sel_hi:[1,0]
	v_pk_mul_f32 v[84:85], v[84:85], v[90:91] op_sel_hi:[1,0]
	v_pk_mul_f32 v[92:93], v[82:83], v[90:91] op_sel_hi:[1,0]
	v_pk_mul_f32 v[82:83], v[80:81], v[90:91] op_sel_hi:[1,0]
	v_cvt_pk_bf16_f32 v80, v84, v85
	v_cvt_pk_bf16_f32 v81, v86, v87
	v_cvt_pk_bf16_f32 v82, v82, v83
	v_cvt_pk_bf16_f32 v83, v92, v93
	global_store_dwordx4 v[88:89], v[80:83], off offset:256
.LBB0_754:
	s_or_b64 exec, exec, s[38:39]
	s_nop 0
	v_or_b32_e32 v82, 48, v134
	v_ashrrev_i32_e32 v83, 31, v82
	v_mad_i64_i32 v[80:81], s[8:9], v82, s65, 0
	v_lshl_add_u64 v[80:81], s[10:11], 0, v[80:81]
	v_lshl_add_u64 v[82:83], v[82:83], 2, s[12:13]
	s_and_saveexec_b64 s[38:39], vcc
	s_cbranch_execz .LBB0_756
	v_mov_b32_e32 v84, v243
	v_fmamk_f32 v84, v84, 0x3a800000, v146
	v_mul_f32_e32 v85, 0x4b800000, v84
	v_cmp_gt_f32_e64 s[8:9], s67, v84
	s_nop 1
	v_cndmask_b32_e64 v84, v84, v85, s[8:9]
	v_rsq_f32_e32 v86, v84
	v_lshl_add_u64 v[84:85], v[132:133], 1, v[80:81]
	v_mul_f32_e32 v87, 0x45800000, v86
	v_cndmask_b32_e64 v86, v86, v87, s[8:9]
	v_pk_mul_f32 v[78:79], v[78:79], v[86:87] op_sel_hi:[1,0]
	v_pk_mul_f32 v[76:77], v[76:77], v[86:87] op_sel_hi:[1,0]
	v_pk_mul_f32 v[88:89], v[74:75], v[86:87] op_sel_hi:[1,0]
	v_pk_mul_f32 v[74:75], v[72:73], v[86:87] op_sel_hi:[1,0]
	v_cvt_pk_bf16_f32 v72, v76, v77
	v_cvt_pk_bf16_f32 v73, v78, v79
	v_cvt_pk_bf16_f32 v74, v74, v75
	v_cvt_pk_bf16_f32 v75, v88, v89
	global_store_dwordx4 v[84:85], v[72:75], off
.LBB0_756:
	s_or_b64 exec, exec, s[38:39]
	s_and_saveexec_b64 s[38:39], s[4:5]
	s_cbranch_execz .LBB0_758
	v_mov_b32_e32 v72, v243
	v_fmamk_f32 v72, v72, 0x3a800000, v146
	v_mul_f32_e32 v73, 0x4b800000, v72
	v_cmp_gt_f32_e64 s[8:9], s67, v72
	s_nop 1
	v_cndmask_b32_e64 v72, v72, v73, s[8:9]
	v_rsq_f32_e32 v74, v72
	v_lshl_add_u64 v[72:73], v[132:133], 1, v[80:81]
	v_mul_f32_e32 v75, 0x45800000, v74
	v_cndmask_b32_e64 v74, v74, v75, s[8:9]
	v_pk_mul_f32 v[70:71], v[70:71], v[74:75] op_sel_hi:[1,0]
	v_pk_mul_f32 v[68:69], v[68:69], v[74:75] op_sel_hi:[1,0]
	v_pk_mul_f32 v[76:77], v[66:67], v[74:75] op_sel_hi:[1,0]
	v_pk_mul_f32 v[66:67], v[64:65], v[74:75] op_sel_hi:[1,0]
	v_cvt_pk_bf16_f32 v64, v68, v69
	v_cvt_pk_bf16_f32 v65, v70, v71
	v_cvt_pk_bf16_f32 v66, v66, v67
	v_cvt_pk_bf16_f32 v67, v76, v77
	global_store_dwordx4 v[72:73], v[64:67], off offset:256
.LBB0_758:
	s_or_b64 exec, exec, s[38:39]
	s_nop 0
	v_add_u32_e32 v66, 0x80, v134
	v_ashrrev_i32_e32 v67, 31, v66
	v_mad_i64_i32 v[64:65], s[8:9], v66, s65, 0
	v_lshl_add_u64 v[64:65], s[10:11], 0, v[64:65]
	v_lshl_add_u64 v[66:67], v[66:67], 2, s[12:13]
	s_and_saveexec_b64 s[38:39], vcc
	s_cbranch_execz .LBB0_760
	v_mov_b32_e32 v68, v244
	v_fmamk_f32 v68, v68, 0x3a800000, v146
	v_mul_f32_e32 v69, 0x4b800000, v68
	v_cmp_gt_f32_e64 s[8:9], s67, v68
	s_nop 1
	v_cndmask_b32_e64 v68, v68, v69, s[8:9]
	v_rsq_f32_e32 v70, v68
	v_lshl_add_u64 v[68:69], v[132:133], 1, v[64:65]
	v_mul_f32_e32 v71, 0x45800000, v70
	v_cndmask_b32_e64 v70, v70, v71, s[8:9]
	v_pk_mul_f32 v[62:63], v[62:63], v[70:71] op_sel_hi:[1,0]
	v_pk_mul_f32 v[60:61], v[60:61], v[70:71] op_sel_hi:[1,0]
	v_pk_mul_f32 v[72:73], v[58:59], v[70:71] op_sel_hi:[1,0]
	v_pk_mul_f32 v[58:59], v[56:57], v[70:71] op_sel_hi:[1,0]
	v_cvt_pk_bf16_f32 v56, v60, v61
	v_cvt_pk_bf16_f32 v57, v62, v63
	v_cvt_pk_bf16_f32 v58, v58, v59
	v_cvt_pk_bf16_f32 v59, v72, v73
	global_store_dwordx4 v[68:69], v[56:59], off
.LBB0_760:
	s_or_b64 exec, exec, s[38:39]
	s_and_saveexec_b64 s[38:39], s[4:5]
	s_cbranch_execz .LBB0_762
	v_mov_b32_e32 v56, v244
	v_fmamk_f32 v56, v56, 0x3a800000, v146
	v_mul_f32_e32 v57, 0x4b800000, v56
	v_cmp_gt_f32_e64 s[8:9], s67, v56
	s_nop 1
	v_cndmask_b32_e64 v56, v56, v57, s[8:9]
	v_rsq_f32_e32 v58, v56
	v_lshl_add_u64 v[56:57], v[132:133], 1, v[64:65]
	v_mul_f32_e32 v59, 0x45800000, v58
	v_cndmask_b32_e64 v58, v58, v59, s[8:9]
	v_pk_mul_f32 v[54:55], v[54:55], v[58:59] op_sel_hi:[1,0]
	v_pk_mul_f32 v[52:53], v[52:53], v[58:59] op_sel_hi:[1,0]
	v_pk_mul_f32 v[60:61], v[50:51], v[58:59] op_sel_hi:[1,0]
	v_pk_mul_f32 v[50:51], v[48:49], v[58:59] op_sel_hi:[1,0]
	v_cvt_pk_bf16_f32 v48, v52, v53
	v_cvt_pk_bf16_f32 v49, v54, v55
	v_cvt_pk_bf16_f32 v50, v50, v51
	v_cvt_pk_bf16_f32 v51, v60, v61
	global_store_dwordx4 v[56:57], v[48:51], off offset:256
; DI unsigned cvtpk(float lo, float hi) { f32x2 v = {lo, hi}; bfv2 r = __builtin_convertvector(v, bfv2); return __builtin_bit_cast(unsigned, r); }
;     DI void operator()(const f32x4 (&acc)[2][2][4][2], const Unit& u, int wr, int wc, int fr, int fq) const {
; #pragma unroll
;         for (int ai = 0; ai < 2; ++ai)
; #pragma unroll
;             for (int m = 0; m < 4; ++m) {
;                 const int r = u.pm * BM + ai * HALF + wr * 64 + m * 16 + fr;
; #pragma unroll
;                 for (int bj = 0; bj < 2; ++bj) f(r, u.pn * BM + bj * HALF + wc * 32 + 8 * fq, acc[ai][bj][m][0], acc[ai][bj][m][1]);
;                 asm volatile("" ::: "memory");
;             }
;     }
; DI void st_bf8(bf16_t* p, f32x4 a, f32x4 b) { u32x4 o = {cvtpk(a[0], a[1]), cvtpk(a[2], a[3]), cvtpk(b[0], b[1]), cvtpk(b[2], b[3])}; *(u32x4*)p = o; }
.LBB0_762:
	s_or_b64 exec, exec, s[38:39]
	s_nop 0
	v_add_u32_e32 v50, 0x90, v134
	v_ashrrev_i32_e32 v51, 31, v50
	v_mad_i64_i32 v[48:49], s[8:9], v50, s65, 0
	v_lshl_add_u64 v[48:49], s[10:11], 0, v[48:49]
	v_lshl_add_u64 v[50:51], v[50:51], 2, s[12:13]
	s_and_saveexec_b64 s[38:39], vcc
	s_cbranch_execz .LBB0_764
	v_mov_b32_e32 v52, v245
	v_fmamk_f32 v52, v52, 0x3a800000, v146
	v_mul_f32_e32 v53, 0x4b800000, v52
	v_cmp_gt_f32_e64 s[8:9], s67, v52
	s_nop 1
	v_cndmask_b32_e64 v52, v52, v53, s[8:9]
	v_rsq_f32_e32 v54, v52
	v_lshl_add_u64 v[52:53], v[132:133], 1, v[48:49]
	v_mul_f32_e32 v55, 0x45800000, v54
	v_cndmask_b32_e64 v54, v54, v55, s[8:9]
	v_pk_mul_f32 v[46:47], v[46:47], v[54:55] op_sel_hi:[1,0]
	v_pk_mul_f32 v[44:45], v[44:45], v[54:55] op_sel_hi:[1,0]
	v_pk_mul_f32 v[56:57], v[42:43], v[54:55] op_sel_hi:[1,0]
	v_pk_mul_f32 v[42:43], v[40:41], v[54:55] op_sel_hi:[1,0]
	v_cvt_pk_bf16_f32 v40, v44, v45
	v_cvt_pk_bf16_f32 v41, v46, v47
	v_cvt_pk_bf16_f32 v42, v42, v43
	v_cvt_pk_bf16_f32 v43, v56, v57
	global_store_dwordx4 v[52:53], v[40:43], off
.LBB0_764:
	s_or_b64 exec, exec, s[38:39]
	s_and_saveexec_b64 s[38:39], s[4:5]
	s_cbranch_execz .LBB0_766
	v_mov_b32_e32 v40, v245
	v_fmamk_f32 v40, v40, 0x3a800000, v146
	v_mul_f32_e32 v41, 0x4b800000, v40
	v_cmp_gt_f32_e64 s[8:9], s67, v40
	s_nop 1
	v_cndmask_b32_e64 v40, v40, v41, s[8:9]
	v_rsq_f32_e32 v42, v40
	v_lshl_add_u64 v[40:41], v[132:133], 1, v[48:49]
	v_mul_f32_e32 v43, 0x45800000, v42
	v_cndmask_b32_e64 v42, v42, v43, s[8:9]
	v_pk_mul_f32 v[38:39], v[38:39], v[42:43] op_sel_hi:[1,0]
	v_pk_mul_f32 v[36:37], v[36:37], v[42:43] op_sel_hi:[1,0]
	v_pk_mul_f32 v[44:45], v[34:35], v[42:43] op_sel_hi:[1,0]
	v_pk_mul_f32 v[34:35], v[32:33], v[42:43] op_sel_hi:[1,0]
	v_cvt_pk_bf16_f32 v32, v36, v37
	v_cvt_pk_bf16_f32 v33, v38, v39
	v_cvt_pk_bf16_f32 v34, v34, v35
	v_cvt_pk_bf16_f32 v35, v44, v45
	global_store_dwordx4 v[40:41], v[32:35], off offset:256
.LBB0_766:
	s_or_b64 exec, exec, s[38:39]
	s_nop 0
	v_add_u32_e32 v34, 0xa0, v134
	v_ashrrev_i32_e32 v35, 31, v34
	v_mad_i64_i32 v[32:33], s[8:9], v34, s65, 0
	v_lshl_add_u64 v[32:33], s[10:11], 0, v[32:33]
	v_lshl_add_u64 v[34:35], v[34:35], 2, s[12:13]
	s_and_saveexec_b64 s[38:39], vcc
	s_cbranch_execz .LBB0_768
	v_mov_b32_e32 v36, v246
	v_fmamk_f32 v36, v36, 0x3a800000, v146
	v_mul_f32_e32 v37, 0x4b800000, v36
	v_cmp_gt_f32_e64 s[8:9], s67, v36
	s_nop 1
	v_cndmask_b32_e64 v36, v36, v37, s[8:9]
	v_rsq_f32_e32 v38, v36
	v_lshl_add_u64 v[36:37], v[132:133], 1, v[32:33]
	v_mul_f32_e32 v39, 0x45800000, v38
	v_cndmask_b32_e64 v38, v38, v39, s[8:9]
	v_pk_mul_f32 v[30:31], v[30:31], v[38:39] op_sel_hi:[1,0]
	v_pk_mul_f32 v[28:29], v[28:29], v[38:39] op_sel_hi:[1,0]
	v_pk_mul_f32 v[40:41], v[26:27], v[38:39] op_sel_hi:[1,0]
	v_pk_mul_f32 v[26:27], v[24:25], v[38:39] op_sel_hi:[1,0]
	v_cvt_pk_bf16_f32 v24, v28, v29
	v_cvt_pk_bf16_f32 v25, v30, v31
	v_cvt_pk_bf16_f32 v26, v26, v27
	v_cvt_pk_bf16_f32 v27, v40, v41
	global_store_dwordx4 v[36:37], v[24:27], off
.LBB0_768:
	s_or_b64 exec, exec, s[38:39]
	s_and_saveexec_b64 s[38:39], s[4:5]
	s_cbranch_execz .LBB0_770
	v_mov_b32_e32 v24, v246
	v_fmamk_f32 v24, v24, 0x3a800000, v146
	v_mul_f32_e32 v25, 0x4b800000, v24
	v_cmp_gt_f32_e64 s[8:9], s67, v24
	s_nop 1
	v_cndmask_b32_e64 v24, v24, v25, s[8:9]
	v_rsq_f32_e32 v26, v24
	v_lshl_add_u64 v[24:25], v[132:133], 1, v[32:33]
	v_mul_f32_e32 v27, 0x45800000, v26
	v_cndmask_b32_e64 v26, v26, v27, s[8:9]
	v_pk_mul_f32 v[22:23], v[22:23], v[26:27] op_sel_hi:[1,0]
	v_pk_mul_f32 v[20:21], v[20:21], v[26:27] op_sel_hi:[1,0]
	v_pk_mul_f32 v[28:29], v[18:19], v[26:27] op_sel_hi:[1,0]
	v_pk_mul_f32 v[18:19], v[16:17], v[26:27] op_sel_hi:[1,0]
	v_cvt_pk_bf16_f32 v16, v20, v21
	v_cvt_pk_bf16_f32 v17, v22, v23
	v_cvt_pk_bf16_f32 v18, v18, v19
	v_cvt_pk_bf16_f32 v19, v28, v29
	global_store_dwordx4 v[24:25], v[16:19], off offset:256
.LBB0_770:
	s_or_b64 exec, exec, s[38:39]
	s_nop 0
	v_add_u32_e32 v18, 0xb0, v134
	v_ashrrev_i32_e32 v19, 31, v18
	v_mad_i64_i32 v[16:17], s[8:9], v18, s65, 0
	v_lshl_add_u64 v[16:17], s[10:11], 0, v[16:17]
	v_lshl_add_u64 v[18:19], v[18:19], 2, s[12:13]
	s_and_saveexec_b64 s[8:9], vcc
	s_cbranch_execz .LBB0_772
	v_mov_b32_e32 v20, v247
	v_fmamk_f32 v20, v20, 0x3a800000, v146
	v_mul_f32_e32 v21, 0x4b800000, v20
	v_cmp_gt_f32_e32 vcc, s67, v20
	s_nop 1
	v_cndmask_b32_e32 v20, v20, v21, vcc
	v_rsq_f32_e32 v22, v20
	v_lshl_add_u64 v[20:21], v[132:133], 1, v[16:17]
	v_mul_f32_e32 v23, 0x45800000, v22
	v_cndmask_b32_e32 v22, v22, v23, vcc
	v_pk_mul_f32 v[14:15], v[14:15], v[22:23] op_sel_hi:[1,0]
	v_pk_mul_f32 v[12:13], v[12:13], v[22:23] op_sel_hi:[1,0]
	v_pk_mul_f32 v[24:25], v[10:11], v[22:23] op_sel_hi:[1,0]
	v_pk_mul_f32 v[10:11], v[8:9], v[22:23] op_sel_hi:[1,0]
	v_cvt_pk_bf16_f32 v8, v12, v13
	v_cvt_pk_bf16_f32 v9, v14, v15
	v_cvt_pk_bf16_f32 v10, v10, v11
	v_cvt_pk_bf16_f32 v11, v24, v25
	global_store_dwordx4 v[20:21], v[8:11], off
.LBB0_772:
	s_or_b64 exec, exec, s[8:9]
	s_and_saveexec_b64 s[8:9], s[4:5]
	s_cbranch_execz .LBB0_774
	v_mov_b32_e32 v8, v247
	v_fmamk_f32 v8, v8, 0x3a800000, v146
	v_mul_f32_e32 v9, 0x4b800000, v8
	v_cmp_gt_f32_e32 vcc, s67, v8
	s_nop 1
	v_cndmask_b32_e32 v8, v8, v9, vcc
	v_rsq_f32_e32 v10, v8
	v_lshl_add_u64 v[8:9], v[132:133], 1, v[16:17]
	v_mul_f32_e32 v11, 0x45800000, v10
	v_cndmask_b32_e32 v10, v10, v11, vcc
	v_pk_mul_f32 v[6:7], v[6:7], v[10:11] op_sel_hi:[1,0]
	v_pk_mul_f32 v[4:5], v[4:5], v[10:11] op_sel_hi:[1,0]
	v_pk_mul_f32 v[12:13], v[2:3], v[10:11] op_sel_hi:[1,0]
	v_pk_mul_f32 v[2:3], v[0:1], v[10:11] op_sel_hi:[1,0]
	v_cvt_pk_bf16_f32 v0, v4, v5
	v_cvt_pk_bf16_f32 v1, v6, v7
	v_cvt_pk_bf16_f32 v2, v2, v3
	v_cvt_pk_bf16_f32 v3, v12, v13
	global_store_dwordx4 v[8:9], v[0:3], off offset:256

; DI void phase_ffn_act(const Params& p, int slab) {
;     ...
;     const int seglen = (MSLAB + tpg - 1) / tpg;
;     const int t_beg = sidx * seglen, t_end = min(MSLAB, t_beg + seglen);
;     const int c8 = cg8 * 8, m0 = slab * MSLAB;
;     if (c8 >= DFF) { for (int ml = t_beg; ml < t_end; ++ml) *(u32x4*)(act + (size_t)ml * DFFP + c8) = (u32x4){0u, 0u, 0u, 0u}; return; }
;     float wg[3][8], wu[3][8], bg[8], bu[8];
; #pragma unroll
;     for (int e = 0; e < 8; ++e) { bg[e] = p.ffn_conv_b[c8 + e]; bu[e] = p.ffn_conv_b[DFF + c8 + e]; }
; #pragma unroll
;     for (int j = 0; j < 3; ++j)
; #pragma unroll
;         for (int e = 0; e < 8; ++e) { wg[j][e] = p.ffn_conv_w[(size_t)j * DFF2 + c8 + e]; wu[j][e] = p.ffn_conv_w[(size_t)j * DFF2 + DFF + c8 + e]; }
;     auto ldrow = [&](int ml, u32x4& g, u32x4& u) {
;         if (ml >= 0 && ml < MSLAB) { const bf16_t* row = us + (size_t)ml * DFF2; g = *(const u32x4*)(row + c8); u = *(const u32x4*)(row + DFF + c8); }
;         else { g = (u32x4){0u, 0u, 0u, 0u}; u = g; }
;     };
;     u32x4 gp, up, gc, uc, gn, un, gn2, un2, gn3, un3, gn4, un4;
;     ldrow(t_beg - 1, gp, up); ldrow(t_beg, gc, uc); ldrow(t_beg + 1, gn, un); ldrow(t_beg + 2, gn2, un2); ldrow(t_beg + 3, gn3, un3);
;     for (int ml = t_beg; ml < t_end; ++ml) {
;         ldrow(ml + 4, gn4, un4);
.LBB0_796:
	s_or_b64 exec, exec, s[14:15]
	v_cmp_lt_i32_e32 vcc, v122, v123
	s_and_saveexec_b64 s[14:15], vcc
	s_cbranch_execz .LBB0_801
	v_lshlrev_b64 v[106:107], 1, v[0:1]
	s_movk_i32 s16, 0x1600
	v_mad_i64_i32 v[106:107], s[16:17], v122, s16, v[106:107]
	v_lshl_add_u64 v[106:107], s[28:29], 0, v[106:107]
	s_mov_b64 s[16:17], 0x2dd20000
	v_lshl_add_u64 v[118:119], v[106:107], 0, s[16:17]
	s_movk_i32 s16, 0x1580
	v_mul_lo_u32 v106, v122, s16
	v_add_u32_e32 v120, 0x5600, v106
	s_mov_b64 s[16:17], 0
	s_mov_b32 s22, 0xc000
	v_mov_b32_e32 v106, 0
	s_movk_i32 s23, 0x7ff
	s_mov_b64 s[18:19], 0x1600
	s_mov_b32 s24, 0
	s_waitcnt vmcnt(0)
	s_branch .LBB0_799
.LBB0_799:
	s_cmp_eq_u32 s24, 0
	s_cbranch_scc1 .Lffaa_e_st
	s_waitcnt vmcnt(0)
	s_branch .Lffaa_e_go
.Lffaa_e_st:
	s_waitcnt vmcnt(4)
.Lffaa_e_go:
	v_mov_b64_e32 v[110:111], v[78:79]
	v_mov_b64_e32 v[112:113], v[80:81]
	v_mov_b64_e32 v[114:115], v[94:95]
	v_mov_b64_e32 v[116:117], v[96:97]
	v_add_u32_e32 v201, 4, v122
	v_mov_b32_e32 v107, v106
	v_cmp_gt_u32_e32 vcc, s22, v201
	v_mov_b32_e32 v108, v106
	v_mov_b32_e32 v109, v106
	v_mov_b64_e32 v[78:79], v[106:107]
	v_mov_b64_e32 v[94:95], v[106:107]
	v_mov_b64_e32 v[80:81], v[108:109]
	v_mov_b64_e32 v[96:97], v[108:109]
	s_and_saveexec_b64 s[20:21], vcc
	s_cbranch_execz .Lffaa_e_skip
	v_mov_b32_e32 v121, v106
	v_lshl_add_u64 v[202:203], v[120:121], 1, s[10:11]
	v_lshl_add_u64 v[202:203], v[0:1], 1, v[202:203]
	v_add_co_u32_e32 v204, vcc, 0x1000, v202
	s_nop 1
	v_addc_co_u32_e32 v205, vcc, 0, v203, vcc
	global_load_dwordx4 v[78:81], v[202:203], off
	s_nop 0
	global_load_dwordx4 v[94:97], v[204:205], off offset:1408
; DI unsigned cvtpk(float lo, float hi) { f32x2 v = {lo, hi}; bfv2 r = __builtin_convertvector(v, bfv2); return __builtin_bit_cast(unsigned, r); }
; DI float bflo(unsigned w) { return __uint_as_float(w << 16); }
; DI float bfhi(unsigned w) { return __uint_as_float(w & 0xffff0000u); }
; DI float silu_f(float v) { return v * __builtin_amdgcn_rcpf(1.f + __expf(-v)); }
; DI void seq_of(int m, int& base, int& t, int& T) { if (m < MP) { base = m & ~2047; t = m & 2047; T = 2048; } else { int r = m - MP; base = MP + (r & ~16383); t = r & 16383; T = 16384; } }
; DI void phase_ffn_act(const Params& p, int slab) {
;     ...
;     for (int ml = t_beg; ml < t_end; ++ml) {
;         ldrow(ml + 4, gn4, un4);
;         int base, t, T; seq_of(m0 + ml, base, t, T);
;         const float mp = t > 0 ? 1.f : 0.f, mn = t + 1 < T ? 1.f : 0.f;
;         const unsigned gpa[4] = {gp.x, gp.y, gp.z, gp.w}, gca[4] = {gc.x, gc.y, gc.z, gc.w}, gna[4] = {gn.x, gn.y, gn.z, gn.w};
;         const unsigned upa[4] = {up.x, up.y, up.z, up.w}, uca[4] = {uc.x, uc.y, uc.z, uc.w}, una[4] = {un.x, un.y, un.z, un.w};
;         float r[8];
; #pragma unroll
;         for (int e = 0; e < 4; ++e) {
;             const float g0 = bg[2 * e] + mp * bflo(gpa[e]) * wg[0][2 * e] + bflo(gca[e]) * wg[1][2 * e] + mn * bflo(gna[e]) * wg[2][2 * e];
;             const float g1 = bg[2 * e + 1] + mp * bfhi(gpa[e]) * wg[0][2 * e + 1] + bfhi(gca[e]) * wg[1][2 * e + 1] + mn * bfhi(gna[e]) * wg[2][2 * e + 1];
;             const float u0 = bu[2 * e] + mp * bflo(upa[e]) * wu[0][2 * e] + bflo(uca[e]) * wu[1][2 * e] + mn * bflo(una[e]) * wu[2][2 * e];
;             const float u1 = bu[2 * e + 1] + mp * bfhi(upa[e]) * wu[0][2 * e + 1] + bfhi(uca[e]) * wu[1][2 * e + 1] + mn * bfhi(una[e]) * wu[2][2 * e + 1];
;             r[2 * e] = silu_f(g0) * u0; r[2 * e + 1] = silu_f(g1) * u1;
;         }
;         *(u32x4*)(act + (size_t)ml * DFFP + c8) = (u32x4){cvtpk(r[0], r[1]), cvtpk(r[2], r[3]), cvtpk(r[4], r[5]), cvtpk(r[6], r[7])};
;         gp = gc; up = uc; gc = gn; uc = un; gn = gn2; un = un2; gn2 = gn3; un2 = un3; gn3 = gn4; un3 = un4;
;     }
.Lffaa_e_body:
	s_or_b64 exec, exec, s[20:21]
	v_and_b32_e32 v107, 0x7ff, v122
	v_cmp_eq_u32_e32 vcc, 0, v107
	v_lshlrev_b32_e32 v126, 16, v82
	v_and_b32_e32 v127, 0xffff0000, v82
	v_cndmask_b32_e64 v108, 1.0, 0, vcc
	v_pk_mul_f32 v[126:127], v[108:109], v[126:127] op_sel_hi:[0,1]
	v_cmp_eq_u32_e32 vcc, s23, v107
	v_pk_fma_f32 v[126:127], v[22:23], v[126:127], v[6:7]
	v_lshlrev_b32_e32 v128, 16, v66
	v_and_b32_e32 v129, 0xffff0000, v66
	v_cndmask_b32_e64 v124, 1.0, 0, vcc
	v_pk_fma_f32 v[126:127], v[30:31], v[128:129], v[126:127]
	v_lshlrev_b32_e32 v128, 16, v86
	v_and_b32_e32 v129, 0xffff0000, v86
	v_pk_mul_f32 v[128:129], v[124:125], v[128:129] op_sel_hi:[0,1]
	v_pk_fma_f32 v[126:127], v[46:47], v[128:129], v[126:127]
	v_lshlrev_b32_e32 v128, 16, v74
	v_and_b32_e32 v129, 0xffff0000, v74
	v_mul_f32_e32 v74, 0xbfb8aa3b, v126
	v_exp_f32_e32 v74, v74
	v_mul_f32_e32 v82, 0xbfb8aa3b, v127
	v_exp_f32_e32 v82, v82
	v_pk_mul_f32 v[128:129], v[108:109], v[128:129] op_sel_hi:[0,1]
	v_add_f32_e32 v74, 1.0, v74
	v_rcp_f32_e32 v132, v74
	v_add_f32_e32 v74, 1.0, v82
	v_rcp_f32_e32 v133, v74
	v_pk_fma_f32 v[128:129], v[26:27], v[128:129], v[10:11]
	v_lshlrev_b32_e32 v130, 16, v70
	v_and_b32_e32 v131, 0xffff0000, v70
	v_pk_fma_f32 v[128:129], v[42:43], v[130:131], v[128:129]
	v_lshlrev_b32_e32 v130, 16, v90
	v_and_b32_e32 v131, 0xffff0000, v90
	v_pk_mul_f32 v[130:131], v[124:125], v[130:131] op_sel_hi:[0,1]
	v_lshlrev_b32_e32 v82, 16, v83
	v_and_b32_e32 v83, 0xffff0000, v83
	v_pk_fma_f32 v[128:129], v[58:59], v[130:131], v[128:129]
	v_pk_mul_f32 v[126:127], v[126:127], v[132:133]
	v_pk_mul_f32 v[82:83], v[108:109], v[82:83] op_sel_hi:[0,1]
	v_pk_mul_f32 v[126:127], v[128:129], v[126:127]
	v_pk_fma_f32 v[82:83], v[24:25], v[82:83], v[8:9]
	v_lshlrev_b32_e32 v128, 16, v67
	v_and_b32_e32 v129, 0xffff0000, v67
	v_pk_fma_f32 v[82:83], v[32:33], v[128:129], v[82:83]
	v_lshlrev_b32_e32 v128, 16, v87
	v_and_b32_e32 v129, 0xffff0000, v87
	v_pk_mul_f32 v[128:129], v[124:125], v[128:129] op_sel_hi:[0,1]
	v_pk_fma_f32 v[82:83], v[48:49], v[128:129], v[82:83]
	v_lshlrev_b32_e32 v74, 16, v75
	v_and_b32_e32 v75, 0xffff0000, v75
	v_mul_f32_e32 v107, 0xbfb8aa3b, v82
	v_pk_mul_f32 v[74:75], v[108:109], v[74:75] op_sel_hi:[0,1]
	v_exp_f32_e32 v107, v107
	v_mul_f32_e32 v109, 0xbfb8aa3b, v83
	v_exp_f32_e32 v109, v109
	v_pk_fma_f32 v[74:75], v[28:29], v[74:75], v[12:13]
	v_add_f32_e32 v107, 1.0, v107
	v_rcp_f32_e32 v130, v107
	v_add_f32_e32 v107, 1.0, v109
	v_rcp_f32_e32 v131, v107
	v_lshlrev_b32_e32 v128, 16, v71
	v_and_b32_e32 v129, 0xffff0000, v71
	v_pk_fma_f32 v[74:75], v[44:45], v[128:129], v[74:75]
	v_lshlrev_b32_e32 v128, 16, v91
	v_and_b32_e32 v129, 0xffff0000, v91
	v_pk_mul_f32 v[128:129], v[124:125], v[128:129] op_sel_hi:[0,1]
	v_pk_fma_f32 v[74:75], v[60:61], v[128:129], v[74:75]
	v_pk_mul_f32 v[82:83], v[82:83], v[130:131]
	v_lshlrev_b32_e32 v128, 16, v68
	v_pk_mul_f32 v[82:83], v[74:75], v[82:83]
	v_lshlrev_b32_e32 v74, 16, v84
	v_and_b32_e32 v75, 0xffff0000, v84
	v_pk_mul_f32 v[74:75], v[108:109], v[74:75] op_sel_hi:[0,1]
	v_pk_fma_f32 v[74:75], v[18:19], v[74:75], v[2:3]
	v_and_b32_e32 v129, 0xffff0000, v68
	v_pk_fma_f32 v[74:75], v[38:39], v[128:129], v[74:75]
	v_lshlrev_b32_e32 v128, 16, v88
	v_and_b32_e32 v129, 0xffff0000, v88
	v_pk_mul_f32 v[128:129], v[124:125], v[128:129] op_sel_hi:[0,1]
	v_pk_fma_f32 v[74:75], v[54:55], v[128:129], v[74:75]
	v_lshlrev_b32_e32 v128, 16, v76
	v_and_b32_e32 v129, 0xffff0000, v76
	v_mul_f32_e32 v76, 0xbfb8aa3b, v74
	v_exp_f32_e32 v76, v76
	v_mul_f32_e32 v84, 0xbfb8aa3b, v75
	v_exp_f32_e32 v84, v84
	v_pk_mul_f32 v[128:129], v[108:109], v[128:129] op_sel_hi:[0,1]
	v_add_f32_e32 v76, 1.0, v76
	v_rcp_f32_e32 v132, v76
	v_add_f32_e32 v76, 1.0, v84
	v_rcp_f32_e32 v133, v76
	v_pk_fma_f32 v[128:129], v[34:35], v[128:129], v[14:15]
	v_lshlrev_b32_e32 v130, 16, v72
	v_and_b32_e32 v131, 0xffff0000, v72
	v_pk_fma_f32 v[128:129], v[50:51], v[130:131], v[128:129]
	v_lshlrev_b32_e32 v130, 16, v92
	v_and_b32_e32 v131, 0xffff0000, v92
	v_pk_mul_f32 v[130:131], v[124:125], v[130:131] op_sel_hi:[0,1]
	v_pk_fma_f32 v[128:129], v[62:63], v[130:131], v[128:129]
	v_pk_mul_f32 v[74:75], v[74:75], v[132:133]
	v_lshlrev_b32_e32 v84, 16, v69
	v_pk_mul_f32 v[128:129], v[128:129], v[74:75]
	v_lshlrev_b32_e32 v74, 16, v85
	v_and_b32_e32 v75, 0xffff0000, v85
	v_pk_mul_f32 v[74:75], v[108:109], v[74:75] op_sel_hi:[0,1]
	v_pk_fma_f32 v[74:75], v[20:21], v[74:75], v[4:5]
	v_and_b32_e32 v85, 0xffff0000, v69
	v_pk_fma_f32 v[74:75], v[40:41], v[84:85], v[74:75]
	v_lshlrev_b32_e32 v84, 16, v89
	v_and_b32_e32 v85, 0xffff0000, v89
	v_lshlrev_b32_e32 v76, 16, v77
	v_and_b32_e32 v77, 0xffff0000, v77
	v_pk_mul_f32 v[84:85], v[124:125], v[84:85] op_sel_hi:[0,1]
	v_pk_mul_f32 v[76:77], v[108:109], v[76:77] op_sel_hi:[0,1]
	v_pk_fma_f32 v[74:75], v[56:57], v[84:85], v[74:75]
	v_pk_fma_f32 v[76:77], v[36:37], v[76:77], v[16:17]
	v_lshlrev_b32_e32 v84, 16, v73
	v_and_b32_e32 v85, 0xffff0000, v73
	v_pk_fma_f32 v[76:77], v[52:53], v[84:85], v[76:77]
	v_mul_f32_e32 v84, 0xbfb8aa3b, v74
	v_exp_f32_e32 v85, v84
	v_mul_f32_e32 v84, 0xbfb8aa3b, v75
	v_exp_f32_e32 v107, v84
	v_lshlrev_b32_e32 v84, 16, v93
	v_add_f32_e32 v85, 1.0, v85
	v_rcp_f32_e32 v108, v85
	v_add_f32_e32 v85, 1.0, v107
	v_rcp_f32_e32 v109, v85
	v_and_b32_e32 v85, 0xffff0000, v93
	v_pk_mul_f32 v[84:85], v[124:125], v[84:85] op_sel_hi:[0,1]
	v_pk_fma_f32 v[76:77], v[64:65], v[84:85], v[76:77]
	v_pk_mul_f32 v[74:75], v[74:75], v[108:109]
	v_add_u32_e32 v122, 1, v122
	v_pk_mul_f32 v[84:85], v[76:77], v[74:75]
	v_cvt_pk_bf16_f32 v74, v126, v127
	v_cvt_pk_bf16_f32 v75, v82, v83
	v_cvt_pk_bf16_f32 v76, v128, v129
	v_cvt_pk_bf16_f32 v77, v84, v85
	global_store_dwordx4 v[118:119], v[74:77], off
	v_mov_b64_e32 v[84:85], v[68:69]
	v_mov_b64_e32 v[82:83], v[66:67]
	v_mov_b64_e32 v[76:77], v[72:73]
	v_mov_b64_e32 v[74:75], v[70:71]
	v_mov_b64_e32 v[66:67], v[86:87]
	v_mov_b64_e32 v[70:71], v[90:91]
	v_cmp_ge_i32_e32 vcc, v122, v123
	v_mov_b64_e32 v[68:69], v[88:89]
	v_mov_b64_e32 v[72:73], v[92:93]
	v_mov_b64_e32 v[90:91], v[114:115]
	v_mov_b64_e32 v[86:87], v[110:111]
	v_lshl_add_u64 v[118:119], v[118:119], 0, s[18:19]
	v_add_u32_e32 v120, 0x1580, v120
	s_or_b64 s[16:17], vcc, s[16:17]
	v_mov_b64_e32 v[92:93], v[116:117]
	v_mov_b64_e32 v[88:89], v[112:113]
	s_andn2_b64 exec, exec, s[16:17]
	s_cbranch_execz .LBB0_801
	s_cmp_eq_u32 s24, 0
	s_cbranch_scc1 .Lffaa_o_st
	s_waitcnt vmcnt(0)
	s_branch .Lffaa_o_go

; DI void phase_ffn_act(const Params& p, int slab) {
;     ...
;     auto ldrow = [&](int ml, u32x4& g, u32x4& u) {
;         if (ml >= 0 && ml < MSLAB) { const bf16_t* row = us + (size_t)ml * DFF2; g = *(const u32x4*)(row + c8); u = *(const u32x4*)(row + DFF + c8); }
;         else { g = (u32x4){0u, 0u, 0u, 0u}; u = g; }
;     };
;     u32x4 gp, up, gc, uc, gn, un, gn2, un2, gn3, un3, gn4, un4;
;     ldrow(t_beg - 1, gp, up); ldrow(t_beg, gc, uc); ldrow(t_beg + 1, gn, un); ldrow(t_beg + 2, gn2, un2); ldrow(t_beg + 3, gn3, un3);
;     for (int ml = t_beg; ml < t_end; ++ml) {
;         ldrow(ml + 4, gn4, un4);
.Lffaa_o_go:
	v_mov_b64_e32 v[110:111], v[98:99]
	v_mov_b64_e32 v[112:113], v[100:101]
	v_mov_b64_e32 v[114:115], v[102:103]
	v_mov_b64_e32 v[116:117], v[104:105]
	v_add_u32_e32 v201, 4, v122
	v_mov_b32_e32 v107, v106
	v_cmp_gt_u32_e32 vcc, s22, v201
	v_mov_b32_e32 v108, v106
	v_mov_b32_e32 v109, v106
	v_mov_b64_e32 v[98:99], v[106:107]
	v_mov_b64_e32 v[102:103], v[106:107]
	v_mov_b64_e32 v[100:101], v[108:109]
	v_mov_b64_e32 v[104:105], v[108:109]
	s_and_saveexec_b64 s[20:21], vcc
	s_cbranch_execz .Lffaa_o_skip
	v_mov_b32_e32 v121, v106
	v_lshl_add_u64 v[202:203], v[120:121], 1, s[10:11]
	v_lshl_add_u64 v[202:203], v[0:1], 1, v[202:203]
	v_add_co_u32_e32 v204, vcc, 0x1000, v202
	s_nop 1
	v_addc_co_u32_e32 v205, vcc, 0, v203, vcc
	global_load_dwordx4 v[98:101], v[202:203], off
	s_nop 0
	global_load_dwordx4 v[102:105], v[204:205], off offset:1408
; DI unsigned cvtpk(float lo, float hi) { f32x2 v = {lo, hi}; bfv2 r = __builtin_convertvector(v, bfv2); return __builtin_bit_cast(unsigned, r); }
; DI float bflo(unsigned w) { return __uint_as_float(w << 16); }
; DI float bfhi(unsigned w) { return __uint_as_float(w & 0xffff0000u); }
; DI float silu_f(float v) { return v * __builtin_amdgcn_rcpf(1.f + __expf(-v)); }
; DI void seq_of(int m, int& base, int& t, int& T) { if (m < MP) { base = m & ~2047; t = m & 2047; T = 2048; } else { int r = m - MP; base = MP + (r & ~16383); t = r & 16383; T = 16384; } }
; DI void phase_ffn_act(const Params& p, int slab) {
;     ...
;     for (int ml = t_beg; ml < t_end; ++ml) {
;         ldrow(ml + 4, gn4, un4);
;         int base, t, T; seq_of(m0 + ml, base, t, T);
;         const float mp = t > 0 ? 1.f : 0.f, mn = t + 1 < T ? 1.f : 0.f;
;         const unsigned gpa[4] = {gp.x, gp.y, gp.z, gp.w}, gca[4] = {gc.x, gc.y, gc.z, gc.w}, gna[4] = {gn.x, gn.y, gn.z, gn.w};
;         const unsigned upa[4] = {up.x, up.y, up.z, up.w}, uca[4] = {uc.x, uc.y, uc.z, uc.w}, una[4] = {un.x, un.y, un.z, un.w};
;         float r[8];
; #pragma unroll
;         for (int e = 0; e < 4; ++e) {
;             const float g0 = bg[2 * e] + mp * bflo(gpa[e]) * wg[0][2 * e] + bflo(gca[e]) * wg[1][2 * e] + mn * bflo(gna[e]) * wg[2][2 * e];
;             const float g1 = bg[2 * e + 1] + mp * bfhi(gpa[e]) * wg[0][2 * e + 1] + bfhi(gca[e]) * wg[1][2 * e + 1] + mn * bfhi(gna[e]) * wg[2][2 * e + 1];
;             const float u0 = bu[2 * e] + mp * bflo(upa[e]) * wu[0][2 * e] + bflo(uca[e]) * wu[1][2 * e] + mn * bflo(una[e]) * wu[2][2 * e];
;             const float u1 = bu[2 * e + 1] + mp * bfhi(upa[e]) * wu[0][2 * e + 1] + bfhi(uca[e]) * wu[1][2 * e + 1] + mn * bfhi(una[e]) * wu[2][2 * e + 1];
;             r[2 * e] = silu_f(g0) * u0; r[2 * e + 1] = silu_f(g1) * u1;
;         }
;         *(u32x4*)(act + (size_t)ml * DFFP + c8) = (u32x4){cvtpk(r[0], r[1]), cvtpk(r[2], r[3]), cvtpk(r[4], r[5]), cvtpk(r[6], r[7])};
;         gp = gc; up = uc; gc = gn; uc = un; gn = gn2; un = un2; gn2 = gn3; un2 = un3; gn3 = gn4; un3 = un4;
;     }
.Lffaa_o_body:
	s_or_b64 exec, exec, s[20:21]
	v_and_b32_e32 v107, 0x7ff, v122
	v_cmp_eq_u32_e32 vcc, 0, v107
	v_lshlrev_b32_e32 v126, 16, v82
	v_and_b32_e32 v127, 0xffff0000, v82
	v_cndmask_b32_e64 v108, 1.0, 0, vcc
	v_pk_mul_f32 v[126:127], v[108:109], v[126:127] op_sel_hi:[0,1]
	v_cmp_eq_u32_e32 vcc, s23, v107
	v_pk_fma_f32 v[126:127], v[22:23], v[126:127], v[6:7]
	v_lshlrev_b32_e32 v128, 16, v66
	v_and_b32_e32 v129, 0xffff0000, v66
	v_cndmask_b32_e64 v124, 1.0, 0, vcc
	v_pk_fma_f32 v[126:127], v[30:31], v[128:129], v[126:127]
	v_lshlrev_b32_e32 v128, 16, v86
	v_and_b32_e32 v129, 0xffff0000, v86
	v_pk_mul_f32 v[128:129], v[124:125], v[128:129] op_sel_hi:[0,1]
	v_pk_fma_f32 v[126:127], v[46:47], v[128:129], v[126:127]
	v_lshlrev_b32_e32 v128, 16, v74
	v_and_b32_e32 v129, 0xffff0000, v74
	v_mul_f32_e32 v74, 0xbfb8aa3b, v126
	v_exp_f32_e32 v74, v74
	v_mul_f32_e32 v82, 0xbfb8aa3b, v127
	v_exp_f32_e32 v82, v82
	v_pk_mul_f32 v[128:129], v[108:109], v[128:129] op_sel_hi:[0,1]
	v_add_f32_e32 v74, 1.0, v74
	v_rcp_f32_e32 v132, v74
	v_add_f32_e32 v74, 1.0, v82
	v_rcp_f32_e32 v133, v74
	v_pk_fma_f32 v[128:129], v[26:27], v[128:129], v[10:11]
	v_lshlrev_b32_e32 v130, 16, v70
	v_and_b32_e32 v131, 0xffff0000, v70
	v_pk_fma_f32 v[128:129], v[42:43], v[130:131], v[128:129]
	v_lshlrev_b32_e32 v130, 16, v90
	v_and_b32_e32 v131, 0xffff0000, v90
	v_pk_mul_f32 v[130:131], v[124:125], v[130:131] op_sel_hi:[0,1]
	v_lshlrev_b32_e32 v82, 16, v83
	v_and_b32_e32 v83, 0xffff0000, v83
	v_pk_fma_f32 v[128:129], v[58:59], v[130:131], v[128:129]
	v_pk_mul_f32 v[126:127], v[126:127], v[132:133]
	v_pk_mul_f32 v[82:83], v[108:109], v[82:83] op_sel_hi:[0,1]
	v_pk_mul_f32 v[126:127], v[128:129], v[126:127]
	v_pk_fma_f32 v[82:83], v[24:25], v[82:83], v[8:9]
	v_lshlrev_b32_e32 v128, 16, v67
	v_and_b32_e32 v129, 0xffff0000, v67
	v_pk_fma_f32 v[82:83], v[32:33], v[128:129], v[82:83]
	v_lshlrev_b32_e32 v128, 16, v87
	v_and_b32_e32 v129, 0xffff0000, v87
	v_pk_mul_f32 v[128:129], v[124:125], v[128:129] op_sel_hi:[0,1]
	v_pk_fma_f32 v[82:83], v[48:49], v[128:129], v[82:83]
	v_lshlrev_b32_e32 v74, 16, v75
	v_and_b32_e32 v75, 0xffff0000, v75
	v_mul_f32_e32 v107, 0xbfb8aa3b, v82
	v_pk_mul_f32 v[74:75], v[108:109], v[74:75] op_sel_hi:[0,1]
	v_exp_f32_e32 v107, v107
	v_mul_f32_e32 v109, 0xbfb8aa3b, v83
	v_exp_f32_e32 v109, v109
	v_pk_fma_f32 v[74:75], v[28:29], v[74:75], v[12:13]
	v_add_f32_e32 v107, 1.0, v107
	v_rcp_f32_e32 v130, v107
	v_add_f32_e32 v107, 1.0, v109
	v_rcp_f32_e32 v131, v107
	v_lshlrev_b32_e32 v128, 16, v71
	v_and_b32_e32 v129, 0xffff0000, v71
	v_pk_fma_f32 v[74:75], v[44:45], v[128:129], v[74:75]
	v_lshlrev_b32_e32 v128, 16, v91
	v_and_b32_e32 v129, 0xffff0000, v91
	v_pk_mul_f32 v[128:129], v[124:125], v[128:129] op_sel_hi:[0,1]
	v_pk_fma_f32 v[74:75], v[60:61], v[128:129], v[74:75]
	v_pk_mul_f32 v[82:83], v[82:83], v[130:131]
	v_lshlrev_b32_e32 v128, 16, v68
	v_pk_mul_f32 v[82:83], v[74:75], v[82:83]
	v_lshlrev_b32_e32 v74, 16, v84
	v_and_b32_e32 v75, 0xffff0000, v84
	v_pk_mul_f32 v[74:75], v[108:109], v[74:75] op_sel_hi:[0,1]
	v_pk_fma_f32 v[74:75], v[18:19], v[74:75], v[2:3]
	v_and_b32_e32 v129, 0xffff0000, v68
	v_pk_fma_f32 v[74:75], v[38:39], v[128:129], v[74:75]
	v_lshlrev_b32_e32 v128, 16, v88
	v_and_b32_e32 v129, 0xffff0000, v88
	v_pk_mul_f32 v[128:129], v[124:125], v[128:129] op_sel_hi:[0,1]
	v_pk_fma_f32 v[74:75], v[54:55], v[128:129], v[74:75]
	v_lshlrev_b32_e32 v128, 16, v76
	v_and_b32_e32 v129, 0xffff0000, v76
	v_mul_f32_e32 v76, 0xbfb8aa3b, v74
	v_exp_f32_e32 v76, v76
	v_mul_f32_e32 v84, 0xbfb8aa3b, v75
	v_exp_f32_e32 v84, v84
	v_pk_mul_f32 v[128:129], v[108:109], v[128:129] op_sel_hi:[0,1]
	v_add_f32_e32 v76, 1.0, v76
	v_rcp_f32_e32 v132, v76
	v_add_f32_e32 v76, 1.0, v84
	v_rcp_f32_e32 v133, v76
	v_pk_fma_f32 v[128:129], v[34:35], v[128:129], v[14:15]
	v_lshlrev_b32_e32 v130, 16, v72
	v_and_b32_e32 v131, 0xffff0000, v72
	v_pk_fma_f32 v[128:129], v[50:51], v[130:131], v[128:129]
	v_lshlrev_b32_e32 v130, 16, v92
	v_and_b32_e32 v131, 0xffff0000, v92
	v_pk_mul_f32 v[130:131], v[124:125], v[130:131] op_sel_hi:[0,1]
	v_pk_fma_f32 v[128:129], v[62:63], v[130:131], v[128:129]
	v_pk_mul_f32 v[74:75], v[74:75], v[132:133]
	v_lshlrev_b32_e32 v84, 16, v69
	v_pk_mul_f32 v[128:129], v[128:129], v[74:75]
	v_lshlrev_b32_e32 v74, 16, v85
	v_and_b32_e32 v75, 0xffff0000, v85
	v_pk_mul_f32 v[74:75], v[108:109], v[74:75] op_sel_hi:[0,1]
	v_pk_fma_f32 v[74:75], v[20:21], v[74:75], v[4:5]
	v_and_b32_e32 v85, 0xffff0000, v69
	v_pk_fma_f32 v[74:75], v[40:41], v[84:85], v[74:75]
	v_lshlrev_b32_e32 v84, 16, v89
	v_and_b32_e32 v85, 0xffff0000, v89
	v_lshlrev_b32_e32 v76, 16, v77
	v_and_b32_e32 v77, 0xffff0000, v77
	v_pk_mul_f32 v[84:85], v[124:125], v[84:85] op_sel_hi:[0,1]
	v_pk_mul_f32 v[76:77], v[108:109], v[76:77] op_sel_hi:[0,1]
	v_pk_fma_f32 v[74:75], v[56:57], v[84:85], v[74:75]
	v_pk_fma_f32 v[76:77], v[36:37], v[76:77], v[16:17]
	v_lshlrev_b32_e32 v84, 16, v73
	v_and_b32_e32 v85, 0xffff0000, v73
	v_pk_fma_f32 v[76:77], v[52:53], v[84:85], v[76:77]
	v_mul_f32_e32 v84, 0xbfb8aa3b, v74
	v_exp_f32_e32 v85, v84
	v_mul_f32_e32 v84, 0xbfb8aa3b, v75
	v_exp_f32_e32 v107, v84
	v_lshlrev_b32_e32 v84, 16, v93
	v_add_f32_e32 v85, 1.0, v85
	v_rcp_f32_e32 v108, v85
	v_add_f32_e32 v85, 1.0, v107
	v_rcp_f32_e32 v109, v85
	v_and_b32_e32 v85, 0xffff0000, v93
	v_pk_mul_f32 v[84:85], v[124:125], v[84:85] op_sel_hi:[0,1]
	v_pk_fma_f32 v[76:77], v[64:65], v[84:85], v[76:77]
	v_pk_mul_f32 v[74:75], v[74:75], v[108:109]
	v_add_u32_e32 v122, 1, v122
	v_pk_mul_f32 v[84:85], v[76:77], v[74:75]
	v_cvt_pk_bf16_f32 v74, v126, v127
	v_cvt_pk_bf16_f32 v75, v82, v83
	v_cvt_pk_bf16_f32 v76, v128, v129
	v_cvt_pk_bf16_f32 v77, v84, v85
	global_store_dwordx4 v[118:119], v[74:77], off
	v_mov_b64_e32 v[84:85], v[68:69]
	v_mov_b64_e32 v[82:83], v[66:67]
	v_mov_b64_e32 v[76:77], v[72:73]
	v_mov_b64_e32 v[74:75], v[70:71]
	v_mov_b64_e32 v[66:67], v[86:87]
	v_mov_b64_e32 v[70:71], v[90:91]
	v_cmp_ge_i32_e32 vcc, v122, v123
	v_mov_b64_e32 v[68:69], v[88:89]
	v_mov_b64_e32 v[72:73], v[92:93]
	v_mov_b64_e32 v[90:91], v[114:115]
	v_mov_b64_e32 v[86:87], v[110:111]
	v_lshl_add_u64 v[118:119], v[118:119], 0, s[18:19]
	v_add_u32_e32 v120, 0x1580, v120
	s_or_b64 s[16:17], vcc, s[16:17]
	v_mov_b64_e32 v[92:93], v[116:117]
	v_mov_b64_e32 v[88:89], v[112:113]
	s_andn2_b64 exec, exec, s[16:17]
	s_cbranch_execz .LBB0_801
	s_branch .LBB0_799
.Lffaa_e_skip:
	s_mov_b32 s24, 1
	s_branch .Lffaa_e_body

; template <class Epi, class Sched, bool ALIGN_EPI = false, bool SP2 = false>
; __device__ __forceinline__ void gemm_phase(PG8_LAS unsigned char* lds, const Gemm g, const Sched& S, const Epi& E) {
;     ...
;         const bool has_next = S.next(ui + 1, nxt);
;         const char* nA = has_next ? (const char*)g.A + (size_t)nxt.pm * tstep : cA; const char* nB = has_next ? (const char*)g.Bt + (size_t)nxt.pn * tstep : cB;
;         for (int t = 0; t < nt; t += 2) {
;             const bool last = (t == nt - 2);
;             const char* a1 = cA + (size_t)(t + 1) * kstep;
;             const char* a2 = last ? nA : cA + (size_t)(t + 2) * kstep; const char* b2 = last ? nB : cB + (size_t)(t + 2) * kstep;
;             const char* a3 = a2 + kstep; const char* b3 = b2 + kstep;
;             if (last && has_next) S.a_ready(nxt);
;             if constexpr (SP2) {
;             PG8_LDB(B0, 0, 0); PG8_LDB(B1, 0, 1); PG8_SCHED; PG8_LDA(At, 0, 0); PG8_STAGE(PG8_SA(1, 1), a1 + hstep, voffA);
;             PG8_WAIT_V(8); PG8_WAIT_L(0); PG8_BAR; PG8_MMA(0, 0, At, B0); PG8_MMA(0, 1, At, B1); PG8_BAR; PG8_SCHED;
;             PG8_LDA(At, 0, 1); PG8_STAGE(PG8_SB(0, 0), b2, voffB); PG8_STAGE(PG8_SB(0, 1), b2 + hstep, voffB); PG8_STAGE(PG8_SA(0, 0), a2, voffA);
;             PG8_WAIT_V(8); PG8_WAIT_L(0); PG8_BAR; PG8_MMA(1, 0, At, B0); PG8_MMA(1, 1, At, B1); PG8_BAR; PG8_SCHED;
;             PG8_LDB(B0, 1, 0); PG8_LDB(B1, 1, 1); PG8_SCHED; PG8_LDA(At, 1, 0); PG8_STAGE(PG8_SA(0, 1), a2 + hstep, voffA);
;             PG8_WAIT_V(8); PG8_WAIT_L(0); PG8_BAR; PG8_MMA(0, 0, At, B0); PG8_MMA(0, 1, At, B1); PG8_BAR; PG8_SCHED;
;             PG8_LDA(At, 1, 1); PG8_STAGE(PG8_SB(1, 0), b3, voffB); PG8_STAGE(PG8_SB(1, 1), b3 + hstep, voffB); PG8_STAGE(PG8_SA(1, 0), a3, voffA);
;             PG8_WAIT_V(8); PG8_WAIT_L(0); PG8_BAR; PG8_MMA(1, 0, At, B0); PG8_MMA(1, 1, At, B1); PG8_BAR; PG8_SCHED;
;             } else {
;             PG8_LDB(B0, 0, 0); PG8_SCHED; PG8_LDA(At, 0, 0); PG8_STAGE(PG8_SA(1, 1), a1 + hstep, voffA);
;             PG8_WAIT_L(8); PG8_BAR; PG8_WAIT_L(0); PG8_MMA(0, 0, At, B0); PG8_BAR; PG8_SCHED;
;             PG8_LDB(B1, 0, 1); PG8_STAGE(PG8_SB(0, 0), b2, voffB);
;             PG8_BAR; PG8_WAIT_L(0); PG8_MMA(0, 1, At, B1); PG8_BAR;
;             PG8_LDA(At, 0, 1); PG8_STAGE(PG8_SA(0, 0), a2, voffA);
;             PG8_BAR; PG8_WAIT_L(0); PG8_MMA(1, 0, At, B0); PG8_BAR; PG8_SCHED;
.LBB0_842:
	s_ashr_i32 s23, s22, 31
	s_lshl_b64 s[26:27], s[22:23], 19
	s_add_u32 s26, s58, s26
	s_addc_u32 s27, s59, s27
	s_and_b64 s[38:39], s[36:37], exec
	s_cselect_b32 s9, s27, s3
	s_cselect_b32 s23, s26, s2
	s_ashr_i32 s25, s24, 31
	s_lshl_b64 s[38:39], s[24:25], 19
	s_add_u32 s38, s49, s38
	s_addc_u32 s39, s50, s39
	s_and_b64 s[44:45], s[36:37], exec
	s_cselect_b32 s25, s39, s43
	s_cselect_b32 s41, s38, s42
	s_add_u32 s2, s2, 0x40080
	s_addc_u32 s3, s3, 0
	s_add_u32 s74, s42, 0x100
	v_mov_b32_e32 v0, 0
	s_addc_u32 s75, s43, 0
	s_mov_b32 s76, -2
	v_mov_b32_e32 v1, v0
	v_mov_b32_e32 v2, v0
	v_mov_b32_e32 v3, v0
	v_mov_b32_e32 v4, v0
	v_mov_b32_e32 v5, v0
	v_mov_b32_e32 v6, v0
	v_mov_b32_e32 v7, v0
	v_mov_b32_e32 v16, v0
	v_mov_b32_e32 v17, v0
	v_mov_b32_e32 v18, v0
	v_mov_b32_e32 v19, v0
	v_mov_b32_e32 v20, v0
	v_mov_b32_e32 v21, v0
	v_mov_b32_e32 v22, v0
	v_mov_b32_e32 v23, v0
	v_mov_b32_e32 v32, v0
	v_mov_b32_e32 v33, v0
	v_mov_b32_e32 v34, v0
	v_mov_b32_e32 v35, v0
	v_mov_b32_e32 v36, v0
	v_mov_b32_e32 v37, v0
	v_mov_b32_e32 v38, v0
	v_mov_b32_e32 v39, v0
	v_mov_b32_e32 v48, v0
	v_mov_b32_e32 v49, v0
	v_mov_b32_e32 v50, v0
	v_mov_b32_e32 v51, v0
	v_mov_b32_e32 v52, v0
	v_mov_b32_e32 v53, v0
	v_mov_b32_e32 v54, v0
	v_mov_b32_e32 v55, v0
	v_mov_b32_e32 v8, v0
	v_mov_b32_e32 v9, v0
	v_mov_b32_e32 v10, v0
	v_mov_b32_e32 v11, v0
	v_mov_b32_e32 v12, v0
	v_mov_b32_e32 v13, v0
	v_mov_b32_e32 v14, v0
	v_mov_b32_e32 v15, v0
	v_mov_b32_e32 v24, v0
	v_mov_b32_e32 v25, v0
	v_mov_b32_e32 v26, v0
	v_mov_b32_e32 v27, v0
	v_mov_b32_e32 v28, v0
	v_mov_b32_e32 v29, v0
	v_mov_b32_e32 v30, v0
	v_mov_b32_e32 v31, v0
	v_mov_b32_e32 v40, v0
	v_mov_b32_e32 v41, v0
	v_mov_b32_e32 v42, v0
	v_mov_b32_e32 v43, v0
	v_mov_b32_e32 v44, v0
	v_mov_b32_e32 v45, v0
	v_mov_b32_e32 v46, v0
	v_mov_b32_e32 v47, v0
	v_mov_b32_e32 v56, v0
	v_mov_b32_e32 v57, v0
	v_mov_b32_e32 v58, v0
	v_mov_b32_e32 v59, v0
	v_mov_b32_e32 v60, v0
	v_mov_b32_e32 v61, v0
	v_mov_b32_e32 v62, v0
	v_mov_b32_e32 v63, v0
	v_mov_b32_e32 v64, v0
	v_mov_b32_e32 v65, v0
	v_mov_b32_e32 v66, v0
	v_mov_b32_e32 v67, v0
	v_mov_b32_e32 v68, v0
	v_mov_b32_e32 v69, v0
	v_mov_b32_e32 v70, v0
	v_mov_b32_e32 v71, v0
	v_mov_b32_e32 v80, v0
	v_mov_b32_e32 v81, v0
	v_mov_b32_e32 v82, v0
	v_mov_b32_e32 v83, v0
	v_mov_b32_e32 v84, v0
	v_mov_b32_e32 v85, v0
	v_mov_b32_e32 v86, v0
	v_mov_b32_e32 v87, v0
	v_mov_b32_e32 v96, v0
	v_mov_b32_e32 v97, v0
	v_mov_b32_e32 v98, v0
	v_mov_b32_e32 v99, v0
	v_mov_b32_e32 v100, v0
	v_mov_b32_e32 v101, v0
	v_mov_b32_e32 v102, v0
	v_mov_b32_e32 v103, v0
	v_mov_b32_e32 v112, v0
	v_mov_b32_e32 v113, v0
	v_mov_b32_e32 v114, v0
	v_mov_b32_e32 v115, v0
	v_mov_b32_e32 v116, v0
	v_mov_b32_e32 v117, v0
	v_mov_b32_e32 v118, v0
	v_mov_b32_e32 v119, v0
	v_mov_b32_e32 v72, v0
	v_mov_b32_e32 v73, v0
	v_mov_b32_e32 v74, v0
	v_mov_b32_e32 v75, v0
	v_mov_b32_e32 v76, v0
	v_mov_b32_e32 v77, v0
	v_mov_b32_e32 v78, v0
	v_mov_b32_e32 v79, v0
	v_mov_b32_e32 v88, v0
	v_mov_b32_e32 v89, v0
	v_mov_b32_e32 v90, v0
	v_mov_b32_e32 v91, v0
	v_mov_b32_e32 v92, v0
	v_mov_b32_e32 v93, v0
	v_mov_b32_e32 v94, v0
	v_mov_b32_e32 v95, v0
	v_mov_b32_e32 v104, v0
	v_mov_b32_e32 v105, v0
	v_mov_b32_e32 v106, v0
	v_mov_b32_e32 v107, v0
	v_mov_b32_e32 v108, v0
	v_mov_b32_e32 v109, v0
	v_mov_b32_e32 v110, v0
	v_mov_b32_e32 v111, v0
	v_mov_b32_e32 v120, v0
	v_mov_b32_e32 v121, v0
	v_mov_b32_e32 v122, v0
	v_mov_b32_e32 v123, v0
	v_mov_b32_e32 v124, v0
	v_mov_b32_e32 v125, v0
	v_mov_b32_e32 v126, v0
	v_mov_b32_e32 v127, v0
	v_lshl_add_u32 v238, s40, 8, v140
	v_ashrrev_i32_e32 v239, 31, v238
	v_lshl_add_u64 v[238:239], v[238:239], 2, s[16:17]
	global_load_dword v240, v[238:239], off
	global_load_dword v241, v[238:239], off offset:64
	global_load_dword v242, v[238:239], off offset:128
	global_load_dword v243, v[238:239], off offset:192
	global_load_dword v244, v[238:239], off offset:512
	global_load_dword v245, v[238:239], off offset:576
	global_load_dword v246, v[238:239], off offset:640
	global_load_dword v247, v[238:239], off offset:704

; DI unsigned cvtpk(float lo, float hi) { f32x2 v = {lo, hi}; bfv2 r = __builtin_convertvector(v, bfv2); return __builtin_bit_cast(unsigned, r); }
;     DI void operator()(const f32x4 (&acc)[2][2][4][2], const Unit& u, int wr, int wc, int fr, int fq) const {
; #pragma unroll
;         for (int ai = 0; ai < 2; ++ai)
; #pragma unroll
;             for (int m = 0; m < 4; ++m) {
;                 const int r = u.pm * BM + ai * HALF + wr * 64 + m * 16 + fr;
; #pragma unroll
;                 for (int bj = 0; bj < 2; ++bj) f(r, u.pn * BM + bj * HALF + wc * 32 + 8 * fq, acc[ai][bj][m][0], acc[ai][bj][m][1]);
;                 asm volatile("" ::: "memory");
;             }
;     }
; DI void st_bf8(bf16_t* p, f32x4 a, f32x4 b) { u32x4 o = {cvtpk(a[0], a[1]), cvtpk(a[2], a[3]), cvtpk(b[0], b[1]), cvtpk(b[2], b[3])}; *(u32x4*)p = o; }
.LBB0_846:
	v_lshl_add_u32 v134, s40, 8, v140
	v_lshl_or_b32 v132, s8, 8, v142
	v_ashrrev_i32_e32 v135, 31, v134
	v_mad_i64_i32 v[136:137], s[2:3], v134, s71, 0
	v_cmp_gt_i32_e32 vcc, s72, v132
	v_lshl_add_u64 v[136:137], s[10:11], 0, v[136:137]
	v_ashrrev_i32_e32 v133, 31, v132
	v_lshl_add_u64 v[138:139], v[134:135], 2, s[16:17]
	s_and_saveexec_b64 s[8:9], vcc
	s_cbranch_execz .LBB0_848
	v_mov_b32_e32 v135, v240
	v_lshl_add_u64 v[150:151], v[132:133], 1, v[136:137]
	v_fmamk_f32 v135, v135, 0x3a800000, v148
	v_mul_f32_e32 v149, 0x4b800000, v135
	v_cmp_gt_f32_e64 s[2:3], s73, v135
	s_nop 1
	v_cndmask_b32_e64 v135, v135, v149, s[2:3]
	v_rsq_f32_e32 v135, v135
	s_nop 0
	v_mul_f32_e32 v149, 0x45800000, v135
	v_cndmask_b32_e64 v152, v135, v149, s[2:3]
	v_pk_mul_f32 v[126:127], v[126:127], v[152:153] op_sel_hi:[1,0]
	v_pk_mul_f32 v[124:125], v[124:125], v[152:153] op_sel_hi:[1,0]
	v_pk_mul_f32 v[154:155], v[122:123], v[152:153] op_sel_hi:[1,0]
	v_pk_mul_f32 v[122:123], v[120:121], v[152:153] op_sel_hi:[1,0]
	v_cvt_pk_bf16_f32 v120, v124, v125
	v_cvt_pk_bf16_f32 v121, v126, v127
	v_cvt_pk_bf16_f32 v122, v122, v123
	v_cvt_pk_bf16_f32 v123, v154, v155
	global_store_dwordx4 v[150:151], v[120:123], off
.LBB0_848:
	s_or_b64 exec, exec, s[8:9]
	s_nop 0
	v_or_b32_e32 v120, 0x80, v132
	v_cmp_gt_i32_e64 s[2:3], s72, v120
	s_and_saveexec_b64 s[40:41], s[2:3]
	s_cbranch_execz .LBB0_850
	v_mov_b32_e32 v120, v240
	v_fmamk_f32 v120, v120, 0x3a800000, v148
	v_mul_f32_e32 v121, 0x4b800000, v120
	v_cmp_gt_f32_e64 s[8:9], s73, v120
	s_nop 1
	v_cndmask_b32_e64 v120, v120, v121, s[8:9]
	v_rsq_f32_e32 v122, v120
	v_lshl_add_u64 v[120:121], v[132:133], 1, v[136:137]
	v_mul_f32_e32 v123, 0x45800000, v122
	v_cndmask_b32_e64 v122, v122, v123, s[8:9]
	v_pk_mul_f32 v[118:119], v[118:119], v[122:123] op_sel_hi:[1,0]
	v_pk_mul_f32 v[116:117], v[116:117], v[122:123] op_sel_hi:[1,0]
	v_pk_mul_f32 v[124:125], v[114:115], v[122:123] op_sel_hi:[1,0]
	v_pk_mul_f32 v[114:115], v[112:113], v[122:123] op_sel_hi:[1,0]
	v_cvt_pk_bf16_f32 v112, v116, v117
	v_cvt_pk_bf16_f32 v113, v118, v119
	v_cvt_pk_bf16_f32 v114, v114, v115
	v_cvt_pk_bf16_f32 v115, v124, v125
	global_store_dwordx4 v[120:121], v[112:115], off offset:256
.LBB0_850:
	s_or_b64 exec, exec, s[40:41]
	s_nop 0
	v_or_b32_e32 v114, 16, v134
	v_ashrrev_i32_e32 v115, 31, v114
	v_mad_i64_i32 v[112:113], s[8:9], v114, s71, 0
	v_lshl_add_u64 v[112:113], s[10:11], 0, v[112:113]
	v_lshl_add_u64 v[114:115], v[114:115], 2, s[16:17]
	s_and_saveexec_b64 s[40:41], vcc
	s_cbranch_execz .LBB0_852
	v_mov_b32_e32 v116, v241
	v_fmamk_f32 v116, v116, 0x3a800000, v148
	v_mul_f32_e32 v117, 0x4b800000, v116
	v_cmp_gt_f32_e64 s[8:9], s73, v116
	s_nop 1
	v_cndmask_b32_e64 v116, v116, v117, s[8:9]
	v_rsq_f32_e32 v118, v116
	v_lshl_add_u64 v[116:117], v[132:133], 1, v[112:113]
	v_mul_f32_e32 v119, 0x45800000, v118
	v_cndmask_b32_e64 v118, v118, v119, s[8:9]
	v_pk_mul_f32 v[110:111], v[110:111], v[118:119] op_sel_hi:[1,0]
	v_pk_mul_f32 v[108:109], v[108:109], v[118:119] op_sel_hi:[1,0]
	v_pk_mul_f32 v[120:121], v[106:107], v[118:119] op_sel_hi:[1,0]
	v_pk_mul_f32 v[106:107], v[104:105], v[118:119] op_sel_hi:[1,0]
	v_cvt_pk_bf16_f32 v104, v108, v109
	v_cvt_pk_bf16_f32 v105, v110, v111
	v_cvt_pk_bf16_f32 v106, v106, v107
	v_cvt_pk_bf16_f32 v107, v120, v121
	global_store_dwordx4 v[116:117], v[104:107], off
.LBB0_852:
	s_or_b64 exec, exec, s[40:41]
	s_and_saveexec_b64 s[40:41], s[2:3]
	s_cbranch_execz .LBB0_854
	v_mov_b32_e32 v104, v241
	v_fmamk_f32 v104, v104, 0x3a800000, v148
	v_mul_f32_e32 v105, 0x4b800000, v104
	v_cmp_gt_f32_e64 s[8:9], s73, v104
	s_nop 1
	v_cndmask_b32_e64 v104, v104, v105, s[8:9]
	v_rsq_f32_e32 v106, v104
	v_lshl_add_u64 v[104:105], v[132:133], 1, v[112:113]
	v_mul_f32_e32 v107, 0x45800000, v106
	v_cndmask_b32_e64 v106, v106, v107, s[8:9]
	v_pk_mul_f32 v[102:103], v[102:103], v[106:107] op_sel_hi:[1,0]
	v_pk_mul_f32 v[100:101], v[100:101], v[106:107] op_sel_hi:[1,0]
	v_pk_mul_f32 v[108:109], v[98:99], v[106:107] op_sel_hi:[1,0]
	v_pk_mul_f32 v[98:99], v[96:97], v[106:107] op_sel_hi:[1,0]
	v_cvt_pk_bf16_f32 v96, v100, v101
	v_cvt_pk_bf16_f32 v97, v102, v103
	v_cvt_pk_bf16_f32 v98, v98, v99
	v_cvt_pk_bf16_f32 v99, v108, v109
	global_store_dwordx4 v[104:105], v[96:99], off offset:256
.LBB0_854:
	s_or_b64 exec, exec, s[40:41]
	s_nop 0
	v_or_b32_e32 v98, 32, v134
	v_ashrrev_i32_e32 v99, 31, v98
	v_mad_i64_i32 v[96:97], s[8:9], v98, s71, 0
	v_lshl_add_u64 v[96:97], s[10:11], 0, v[96:97]
	v_lshl_add_u64 v[98:99], v[98:99], 2, s[16:17]
	s_and_saveexec_b64 s[40:41], vcc
	s_cbranch_execz .LBB0_856
	v_mov_b32_e32 v100, v242
	v_fmamk_f32 v100, v100, 0x3a800000, v148
	v_mul_f32_e32 v101, 0x4b800000, v100
	v_cmp_gt_f32_e64 s[8:9], s73, v100
	s_nop 1
	v_cndmask_b32_e64 v100, v100, v101, s[8:9]
	v_rsq_f32_e32 v102, v100
	v_lshl_add_u64 v[100:101], v[132:133], 1, v[96:97]
	v_mul_f32_e32 v103, 0x45800000, v102
	v_cndmask_b32_e64 v102, v102, v103, s[8:9]
	v_pk_mul_f32 v[94:95], v[94:95], v[102:103] op_sel_hi:[1,0]
	v_pk_mul_f32 v[92:93], v[92:93], v[102:103] op_sel_hi:[1,0]
	v_pk_mul_f32 v[104:105], v[90:91], v[102:103] op_sel_hi:[1,0]
	v_pk_mul_f32 v[90:91], v[88:89], v[102:103] op_sel_hi:[1,0]
	v_cvt_pk_bf16_f32 v88, v92, v93
	v_cvt_pk_bf16_f32 v89, v94, v95
	v_cvt_pk_bf16_f32 v90, v90, v91
	v_cvt_pk_bf16_f32 v91, v104, v105
	global_store_dwordx4 v[100:101], v[88:91], off
; DI unsigned cvtpk(float lo, float hi) { f32x2 v = {lo, hi}; bfv2 r = __builtin_convertvector(v, bfv2); return __builtin_bit_cast(unsigned, r); }
;     DI void operator()(const f32x4 (&acc)[2][2][4][2], const Unit& u, int wr, int wc, int fr, int fq) const {
; #pragma unroll
;         for (int ai = 0; ai < 2; ++ai)
; #pragma unroll
;             for (int m = 0; m < 4; ++m) {
;                 const int r = u.pm * BM + ai * HALF + wr * 64 + m * 16 + fr;
; #pragma unroll
;                 for (int bj = 0; bj < 2; ++bj) f(r, u.pn * BM + bj * HALF + wc * 32 + 8 * fq, acc[ai][bj][m][0], acc[ai][bj][m][1]);
;                 asm volatile("" ::: "memory");
;             }
;     }
; DI void st_bf8(bf16_t* p, f32x4 a, f32x4 b) { u32x4 o = {cvtpk(a[0], a[1]), cvtpk(a[2], a[3]), cvtpk(b[0], b[1]), cvtpk(b[2], b[3])}; *(u32x4*)p = o; }
.LBB0_856:
	s_or_b64 exec, exec, s[40:41]
	s_and_saveexec_b64 s[40:41], s[2:3]
	s_cbranch_execz .LBB0_858
	v_mov_b32_e32 v88, v242
	v_fmamk_f32 v88, v88, 0x3a800000, v148
	v_mul_f32_e32 v89, 0x4b800000, v88
	v_cmp_gt_f32_e64 s[8:9], s73, v88
	s_nop 1
	v_cndmask_b32_e64 v88, v88, v89, s[8:9]
	v_rsq_f32_e32 v90, v88
	v_lshl_add_u64 v[88:89], v[132:133], 1, v[96:97]
	v_mul_f32_e32 v91, 0x45800000, v90
	v_cndmask_b32_e64 v90, v90, v91, s[8:9]
	v_pk_mul_f32 v[86:87], v[86:87], v[90:91] op_sel_hi:[1,0]
	v_pk_mul_f32 v[84:85], v[84:85], v[90:91] op_sel_hi:[1,0]
	v_pk_mul_f32 v[92:93], v[82:83], v[90:91] op_sel_hi:[1,0]
	v_pk_mul_f32 v[82:83], v[80:81], v[90:91] op_sel_hi:[1,0]
	v_cvt_pk_bf16_f32 v80, v84, v85
	v_cvt_pk_bf16_f32 v81, v86, v87
	v_cvt_pk_bf16_f32 v82, v82, v83
	v_cvt_pk_bf16_f32 v83, v92, v93
	global_store_dwordx4 v[88:89], v[80:83], off offset:256
.LBB0_858:
	s_or_b64 exec, exec, s[40:41]
	s_nop 0
	v_or_b32_e32 v82, 48, v134
	v_ashrrev_i32_e32 v83, 31, v82
	v_mad_i64_i32 v[80:81], s[8:9], v82, s71, 0
	v_lshl_add_u64 v[80:81], s[10:11], 0, v[80:81]
	v_lshl_add_u64 v[82:83], v[82:83], 2, s[16:17]
	s_and_saveexec_b64 s[40:41], vcc
	s_cbranch_execz .LBB0_860
	v_mov_b32_e32 v84, v243
	v_fmamk_f32 v84, v84, 0x3a800000, v148
	v_mul_f32_e32 v85, 0x4b800000, v84
	v_cmp_gt_f32_e64 s[8:9], s73, v84
	s_nop 1
	v_cndmask_b32_e64 v84, v84, v85, s[8:9]
	v_rsq_f32_e32 v86, v84
	v_lshl_add_u64 v[84:85], v[132:133], 1, v[80:81]
	v_mul_f32_e32 v87, 0x45800000, v86
	v_cndmask_b32_e64 v86, v86, v87, s[8:9]
	v_pk_mul_f32 v[78:79], v[78:79], v[86:87] op_sel_hi:[1,0]
	v_pk_mul_f32 v[76:77], v[76:77], v[86:87] op_sel_hi:[1,0]
	v_pk_mul_f32 v[88:89], v[74:75], v[86:87] op_sel_hi:[1,0]
	v_pk_mul_f32 v[74:75], v[72:73], v[86:87] op_sel_hi:[1,0]
	v_cvt_pk_bf16_f32 v72, v76, v77
	v_cvt_pk_bf16_f32 v73, v78, v79
	v_cvt_pk_bf16_f32 v74, v74, v75
	v_cvt_pk_bf16_f32 v75, v88, v89
	global_store_dwordx4 v[84:85], v[72:75], off
.LBB0_860:
	s_or_b64 exec, exec, s[40:41]
	s_and_saveexec_b64 s[40:41], s[2:3]
	s_cbranch_execz .LBB0_862
	v_mov_b32_e32 v72, v243
	v_fmamk_f32 v72, v72, 0x3a800000, v148
	v_mul_f32_e32 v73, 0x4b800000, v72
	v_cmp_gt_f32_e64 s[8:9], s73, v72
	s_nop 1
	v_cndmask_b32_e64 v72, v72, v73, s[8:9]
	v_rsq_f32_e32 v74, v72
	v_lshl_add_u64 v[72:73], v[132:133], 1, v[80:81]
	v_mul_f32_e32 v75, 0x45800000, v74
	v_cndmask_b32_e64 v74, v74, v75, s[8:9]
	v_pk_mul_f32 v[70:71], v[70:71], v[74:75] op_sel_hi:[1,0]
	v_pk_mul_f32 v[68:69], v[68:69], v[74:75] op_sel_hi:[1,0]
	v_pk_mul_f32 v[76:77], v[66:67], v[74:75] op_sel_hi:[1,0]
	v_pk_mul_f32 v[66:67], v[64:65], v[74:75] op_sel_hi:[1,0]
	v_cvt_pk_bf16_f32 v64, v68, v69
	v_cvt_pk_bf16_f32 v65, v70, v71
	v_cvt_pk_bf16_f32 v66, v66, v67
	v_cvt_pk_bf16_f32 v67, v76, v77
	global_store_dwordx4 v[72:73], v[64:67], off offset:256
.LBB0_862:
	s_or_b64 exec, exec, s[40:41]
	s_nop 0
	v_add_u32_e32 v66, 0x80, v134
	v_ashrrev_i32_e32 v67, 31, v66
	v_mad_i64_i32 v[64:65], s[8:9], v66, s71, 0
	v_lshl_add_u64 v[64:65], s[10:11], 0, v[64:65]
	v_lshl_add_u64 v[66:67], v[66:67], 2, s[16:17]
	s_and_saveexec_b64 s[40:41], vcc
	s_cbranch_execz .LBB0_864
	v_mov_b32_e32 v68, v244
	v_fmamk_f32 v68, v68, 0x3a800000, v148
	v_mul_f32_e32 v69, 0x4b800000, v68
	v_cmp_gt_f32_e64 s[8:9], s73, v68
	s_nop 1
	v_cndmask_b32_e64 v68, v68, v69, s[8:9]
	v_rsq_f32_e32 v70, v68
	v_lshl_add_u64 v[68:69], v[132:133], 1, v[64:65]
	v_mul_f32_e32 v71, 0x45800000, v70
	v_cndmask_b32_e64 v70, v70, v71, s[8:9]
	v_pk_mul_f32 v[62:63], v[62:63], v[70:71] op_sel_hi:[1,0]
	v_pk_mul_f32 v[60:61], v[60:61], v[70:71] op_sel_hi:[1,0]
	v_pk_mul_f32 v[72:73], v[58:59], v[70:71] op_sel_hi:[1,0]
	v_pk_mul_f32 v[58:59], v[56:57], v[70:71] op_sel_hi:[1,0]
	v_cvt_pk_bf16_f32 v56, v60, v61
	v_cvt_pk_bf16_f32 v57, v62, v63
	v_cvt_pk_bf16_f32 v58, v58, v59
	v_cvt_pk_bf16_f32 v59, v72, v73
	global_store_dwordx4 v[68:69], v[56:59], off
.LBB0_864:
	s_or_b64 exec, exec, s[40:41]
	s_and_saveexec_b64 s[40:41], s[2:3]
	s_cbranch_execz .LBB0_866
	v_mov_b32_e32 v56, v244
	v_fmamk_f32 v56, v56, 0x3a800000, v148
	v_mul_f32_e32 v57, 0x4b800000, v56
	v_cmp_gt_f32_e64 s[8:9], s73, v56
	s_nop 1
	v_cndmask_b32_e64 v56, v56, v57, s[8:9]
	v_rsq_f32_e32 v58, v56
	v_lshl_add_u64 v[56:57], v[132:133], 1, v[64:65]
	v_mul_f32_e32 v59, 0x45800000, v58
	v_cndmask_b32_e64 v58, v58, v59, s[8:9]
	v_pk_mul_f32 v[54:55], v[54:55], v[58:59] op_sel_hi:[1,0]
	v_pk_mul_f32 v[52:53], v[52:53], v[58:59] op_sel_hi:[1,0]
	v_pk_mul_f32 v[60:61], v[50:51], v[58:59] op_sel_hi:[1,0]
	v_pk_mul_f32 v[50:51], v[48:49], v[58:59] op_sel_hi:[1,0]
	v_cvt_pk_bf16_f32 v48, v52, v53
	v_cvt_pk_bf16_f32 v49, v54, v55
	v_cvt_pk_bf16_f32 v50, v50, v51
	v_cvt_pk_bf16_f32 v51, v60, v61
	global_store_dwordx4 v[56:57], v[48:51], off offset:256
; DI unsigned cvtpk(float lo, float hi) { f32x2 v = {lo, hi}; bfv2 r = __builtin_convertvector(v, bfv2); return __builtin_bit_cast(unsigned, r); }
;     DI void operator()(const f32x4 (&acc)[2][2][4][2], const Unit& u, int wr, int wc, int fr, int fq) const {
; #pragma unroll
;         for (int ai = 0; ai < 2; ++ai)
; #pragma unroll
;             for (int m = 0; m < 4; ++m) {
;                 const int r = u.pm * BM + ai * HALF + wr * 64 + m * 16 + fr;
; #pragma unroll
;                 for (int bj = 0; bj < 2; ++bj) f(r, u.pn * BM + bj * HALF + wc * 32 + 8 * fq, acc[ai][bj][m][0], acc[ai][bj][m][1]);
;                 asm volatile("" ::: "memory");
;             }
;     }
; DI void st_bf8(bf16_t* p, f32x4 a, f32x4 b) { u32x4 o = {cvtpk(a[0], a[1]), cvtpk(a[2], a[3]), cvtpk(b[0], b[1]), cvtpk(b[2], b[3])}; *(u32x4*)p = o; }
.LBB0_866:
	s_or_b64 exec, exec, s[40:41]
	s_nop 0
	v_add_u32_e32 v50, 0x90, v134
	v_ashrrev_i32_e32 v51, 31, v50
	v_mad_i64_i32 v[48:49], s[8:9], v50, s71, 0
	v_lshl_add_u64 v[48:49], s[10:11], 0, v[48:49]
	v_lshl_add_u64 v[50:51], v[50:51], 2, s[16:17]
	s_and_saveexec_b64 s[40:41], vcc
	s_cbranch_execz .LBB0_868
	v_mov_b32_e32 v52, v245
	v_fmamk_f32 v52, v52, 0x3a800000, v148
	v_mul_f32_e32 v53, 0x4b800000, v52
	v_cmp_gt_f32_e64 s[8:9], s73, v52
	s_nop 1
	v_cndmask_b32_e64 v52, v52, v53, s[8:9]
	v_rsq_f32_e32 v54, v52
	v_lshl_add_u64 v[52:53], v[132:133], 1, v[48:49]
	v_mul_f32_e32 v55, 0x45800000, v54
	v_cndmask_b32_e64 v54, v54, v55, s[8:9]
	v_pk_mul_f32 v[46:47], v[46:47], v[54:55] op_sel_hi:[1,0]
	v_pk_mul_f32 v[44:45], v[44:45], v[54:55] op_sel_hi:[1,0]
	v_pk_mul_f32 v[56:57], v[42:43], v[54:55] op_sel_hi:[1,0]
	v_pk_mul_f32 v[42:43], v[40:41], v[54:55] op_sel_hi:[1,0]
	v_cvt_pk_bf16_f32 v40, v44, v45
	v_cvt_pk_bf16_f32 v41, v46, v47
	v_cvt_pk_bf16_f32 v42, v42, v43
	v_cvt_pk_bf16_f32 v43, v56, v57
	global_store_dwordx4 v[52:53], v[40:43], off
.LBB0_868:
	s_or_b64 exec, exec, s[40:41]
	s_and_saveexec_b64 s[40:41], s[2:3]
	s_cbranch_execz .LBB0_870
	v_mov_b32_e32 v40, v245
	v_fmamk_f32 v40, v40, 0x3a800000, v148
	v_mul_f32_e32 v41, 0x4b800000, v40
	v_cmp_gt_f32_e64 s[8:9], s73, v40
	s_nop 1
	v_cndmask_b32_e64 v40, v40, v41, s[8:9]
	v_rsq_f32_e32 v42, v40
	v_lshl_add_u64 v[40:41], v[132:133], 1, v[48:49]
	v_mul_f32_e32 v43, 0x45800000, v42
	v_cndmask_b32_e64 v42, v42, v43, s[8:9]
	v_pk_mul_f32 v[38:39], v[38:39], v[42:43] op_sel_hi:[1,0]
	v_pk_mul_f32 v[36:37], v[36:37], v[42:43] op_sel_hi:[1,0]
	v_pk_mul_f32 v[44:45], v[34:35], v[42:43] op_sel_hi:[1,0]
	v_pk_mul_f32 v[34:35], v[32:33], v[42:43] op_sel_hi:[1,0]
	v_cvt_pk_bf16_f32 v32, v36, v37
	v_cvt_pk_bf16_f32 v33, v38, v39
	v_cvt_pk_bf16_f32 v34, v34, v35
	v_cvt_pk_bf16_f32 v35, v44, v45
	global_store_dwordx4 v[40:41], v[32:35], off offset:256
.LBB0_870:
	s_or_b64 exec, exec, s[40:41]
	s_nop 0
	v_add_u32_e32 v34, 0xa0, v134
	v_ashrrev_i32_e32 v35, 31, v34
	v_mad_i64_i32 v[32:33], s[8:9], v34, s71, 0
	v_lshl_add_u64 v[32:33], s[10:11], 0, v[32:33]
	v_lshl_add_u64 v[34:35], v[34:35], 2, s[16:17]
	s_and_saveexec_b64 s[40:41], vcc
	s_cbranch_execz .LBB0_872
	v_mov_b32_e32 v36, v246
	v_fmamk_f32 v36, v36, 0x3a800000, v148
	v_mul_f32_e32 v37, 0x4b800000, v36
	v_cmp_gt_f32_e64 s[8:9], s73, v36
	s_nop 1
	v_cndmask_b32_e64 v36, v36, v37, s[8:9]
	v_rsq_f32_e32 v38, v36
	v_lshl_add_u64 v[36:37], v[132:133], 1, v[32:33]
	v_mul_f32_e32 v39, 0x45800000, v38
	v_cndmask_b32_e64 v38, v38, v39, s[8:9]
	v_pk_mul_f32 v[30:31], v[30:31], v[38:39] op_sel_hi:[1,0]
	v_pk_mul_f32 v[28:29], v[28:29], v[38:39] op_sel_hi:[1,0]
	v_pk_mul_f32 v[40:41], v[26:27], v[38:39] op_sel_hi:[1,0]
	v_pk_mul_f32 v[26:27], v[24:25], v[38:39] op_sel_hi:[1,0]
	v_cvt_pk_bf16_f32 v24, v28, v29
	v_cvt_pk_bf16_f32 v25, v30, v31
	v_cvt_pk_bf16_f32 v26, v26, v27
	v_cvt_pk_bf16_f32 v27, v40, v41
	global_store_dwordx4 v[36:37], v[24:27], off
.LBB0_872:
	s_or_b64 exec, exec, s[40:41]
	s_and_saveexec_b64 s[40:41], s[2:3]
	s_cbranch_execz .LBB0_874
	v_mov_b32_e32 v24, v246
	v_fmamk_f32 v24, v24, 0x3a800000, v148
	v_mul_f32_e32 v25, 0x4b800000, v24
	v_cmp_gt_f32_e64 s[8:9], s73, v24
	s_nop 1
	v_cndmask_b32_e64 v24, v24, v25, s[8:9]
	v_rsq_f32_e32 v26, v24
	v_lshl_add_u64 v[24:25], v[132:133], 1, v[32:33]
	v_mul_f32_e32 v27, 0x45800000, v26
	v_cndmask_b32_e64 v26, v26, v27, s[8:9]
	v_pk_mul_f32 v[22:23], v[22:23], v[26:27] op_sel_hi:[1,0]
	v_pk_mul_f32 v[20:21], v[20:21], v[26:27] op_sel_hi:[1,0]
	v_pk_mul_f32 v[28:29], v[18:19], v[26:27] op_sel_hi:[1,0]
	v_pk_mul_f32 v[18:19], v[16:17], v[26:27] op_sel_hi:[1,0]
	v_cvt_pk_bf16_f32 v16, v20, v21
	v_cvt_pk_bf16_f32 v17, v22, v23
	v_cvt_pk_bf16_f32 v18, v18, v19
	v_cvt_pk_bf16_f32 v19, v28, v29
	global_store_dwordx4 v[24:25], v[16:19], off offset:256
.LBB0_874:
	s_or_b64 exec, exec, s[40:41]
	s_nop 0
	v_add_u32_e32 v18, 0xb0, v134
	v_ashrrev_i32_e32 v19, 31, v18
	v_mad_i64_i32 v[16:17], s[8:9], v18, s71, 0
	v_lshl_add_u64 v[16:17], s[10:11], 0, v[16:17]
	v_lshl_add_u64 v[18:19], v[18:19], 2, s[16:17]
	s_and_saveexec_b64 s[8:9], vcc
	s_cbranch_execz .LBB0_876
	v_mov_b32_e32 v20, v247
	v_fmamk_f32 v20, v20, 0x3a800000, v148
	v_mul_f32_e32 v21, 0x4b800000, v20
	v_cmp_gt_f32_e32 vcc, s73, v20
	s_nop 1
	v_cndmask_b32_e32 v20, v20, v21, vcc
	v_rsq_f32_e32 v22, v20
	v_lshl_add_u64 v[20:21], v[132:133], 1, v[16:17]
	v_mul_f32_e32 v23, 0x45800000, v22
	v_cndmask_b32_e32 v22, v22, v23, vcc
	v_pk_mul_f32 v[14:15], v[14:15], v[22:23] op_sel_hi:[1,0]
	v_pk_mul_f32 v[12:13], v[12:13], v[22:23] op_sel_hi:[1,0]
	v_pk_mul_f32 v[24:25], v[10:11], v[22:23] op_sel_hi:[1,0]
	v_pk_mul_f32 v[10:11], v[8:9], v[22:23] op_sel_hi:[1,0]
	v_cvt_pk_bf16_f32 v8, v12, v13
	v_cvt_pk_bf16_f32 v9, v14, v15
	v_cvt_pk_bf16_f32 v10, v10, v11
	v_cvt_pk_bf16_f32 v11, v24, v25
	global_store_dwordx4 v[20:21], v[8:11], off
.LBB0_876:
	s_or_b64 exec, exec, s[8:9]
	s_and_saveexec_b64 s[8:9], s[2:3]
	s_cbranch_execz .LBB0_878
	v_mov_b32_e32 v8, v247
	v_fmamk_f32 v8, v8, 0x3a800000, v148
	v_mul_f32_e32 v9, 0x4b800000, v8
	v_cmp_gt_f32_e32 vcc, s73, v8
	s_nop 1
	v_cndmask_b32_e32 v8, v8, v9, vcc
	v_rsq_f32_e32 v10, v8
	v_lshl_add_u64 v[8:9], v[132:133], 1, v[16:17]
	v_mul_f32_e32 v11, 0x45800000, v10
	v_cndmask_b32_e32 v10, v10, v11, vcc
	v_pk_mul_f32 v[6:7], v[6:7], v[10:11] op_sel_hi:[1,0]
	v_pk_mul_f32 v[4:5], v[4:5], v[10:11] op_sel_hi:[1,0]
	v_pk_mul_f32 v[12:13], v[2:3], v[10:11] op_sel_hi:[1,0]
	v_pk_mul_f32 v[2:3], v[0:1], v[10:11] op_sel_hi:[1,0]
	v_cvt_pk_bf16_f32 v0, v4, v5
	v_cvt_pk_bf16_f32 v1, v6, v7
	v_cvt_pk_bf16_f32 v2, v2, v3
	v_cvt_pk_bf16_f32 v3, v12, v13
	global_store_dwordx4 v[8:9], v[0:3], off offset:256

; DI void phase_ffn_act(const Params& p, int slab) {
;     ...
;     const int seglen = (MSLAB + tpg - 1) / tpg;
;     const int t_beg = sidx * seglen, t_end = min(MSLAB, t_beg + seglen);
;     const int c8 = cg8 * 8, m0 = slab * MSLAB;
;     if (c8 >= DFF) { for (int ml = t_beg; ml < t_end; ++ml) *(u32x4*)(act + (size_t)ml * DFFP + c8) = (u32x4){0u, 0u, 0u, 0u}; return; }
;     float wg[3][8], wu[3][8], bg[8], bu[8];
; #pragma unroll
;     for (int e = 0; e < 8; ++e) { bg[e] = p.ffn_conv_b[c8 + e]; bu[e] = p.ffn_conv_b[DFF + c8 + e]; }
; #pragma unroll
;     for (int j = 0; j < 3; ++j)
; #pragma unroll
;         for (int e = 0; e < 8; ++e) { wg[j][e] = p.ffn_conv_w[(size_t)j * DFF2 + c8 + e]; wu[j][e] = p.ffn_conv_w[(size_t)j * DFF2 + DFF + c8 + e]; }
;     auto ldrow = [&](int ml, u32x4& g, u32x4& u) {
;         if (ml >= 0 && ml < MSLAB) { const bf16_t* row = us + (size_t)ml * DFF2; g = *(const u32x4*)(row + c8); u = *(const u32x4*)(row + DFF + c8); }
;         else { g = (u32x4){0u, 0u, 0u, 0u}; u = g; }
;     };
;     u32x4 gp, up, gc, uc, gn, un, gn2, un2, gn3, un3, gn4, un4;
;     ldrow(t_beg - 1, gp, up); ldrow(t_beg, gc, uc); ldrow(t_beg + 1, gn, un); ldrow(t_beg + 2, gn2, un2); ldrow(t_beg + 3, gn3, un3);
;     for (int ml = t_beg; ml < t_end; ++ml) {
;         ldrow(ml + 4, gn4, un4);
.LBB0_900:
	s_or_b64 exec, exec, s[8:9]
	v_cmp_lt_i32_e32 vcc, v122, v123
	s_and_saveexec_b64 s[8:9], vcc
	s_cbranch_execz .LBB0_905
	v_lshlrev_b64 v[106:107], 1, v[0:1]
	s_movk_i32 s14, 0x1600
	v_mad_i64_i32 v[106:107], s[14:15], v122, s14, v[106:107]
	v_lshl_add_u64 v[106:107], s[28:29], 0, v[106:107]
	s_mov_b64 s[14:15], 0x2dd20000
	v_lshl_add_u64 v[118:119], v[106:107], 0, s[14:15]
	s_movk_i32 s14, 0x1580
	v_mul_lo_u32 v106, v122, s14
	v_add_u32_e32 v120, 0x5600, v106
	s_mov_b64 s[14:15], 0
	s_mov_b32 s20, 0xc000
	v_mov_b32_e32 v106, 0
	s_movk_i32 s21, 0x4000
	s_mov_b64 s[16:17], 0x1600
	v_mov_b32_e32 v124, 0x3fff
	v_mov_b32_e32 v125, 0x7ff
	v_mov_b32_e32 v126, 0x4000
	v_mov_b32_e32 v127, 0x800
	s_mov_b32 s24, 0
	s_waitcnt vmcnt(0)
	s_branch .LBB0_903

; DI void phase_ffn_act(const Params& p, int slab) {
;     ...
;     auto ldrow = [&](int ml, u32x4& g, u32x4& u) {
;         if (ml >= 0 && ml < MSLAB) { const bf16_t* row = us + (size_t)ml * DFF2; g = *(const u32x4*)(row + c8); u = *(const u32x4*)(row + DFF + c8); }
;         else { g = (u32x4){0u, 0u, 0u, 0u}; u = g; }
;     };
;     u32x4 gp, up, gc, uc, gn, un, gn2, un2, gn3, un3, gn4, un4;
;     ldrow(t_beg - 1, gp, up); ldrow(t_beg, gc, uc); ldrow(t_beg + 1, gn, un); ldrow(t_beg + 2, gn2, un2); ldrow(t_beg + 3, gn3, un3);
;     for (int ml = t_beg; ml < t_end; ++ml) {
;         ldrow(ml + 4, gn4, un4);
.Lffab_e_go:
	v_mov_b64_e32 v[110:111], v[78:79]
	v_mov_b64_e32 v[112:113], v[80:81]
	v_mov_b64_e32 v[114:115], v[94:95]
	v_mov_b64_e32 v[116:117], v[96:97]
	v_add_u32_e32 v201, 4, v122
	v_mov_b32_e32 v107, v106
	v_cmp_gt_u32_e32 vcc, s20, v201
	v_mov_b32_e32 v108, v106
	v_mov_b32_e32 v109, v106
	v_mov_b64_e32 v[78:79], v[106:107]
	v_mov_b64_e32 v[94:95], v[106:107]
	v_mov_b64_e32 v[80:81], v[108:109]
	v_mov_b64_e32 v[96:97], v[108:109]
	s_and_saveexec_b64 s[18:19], vcc
	s_cbranch_execz .Lffab_e_skip
	v_mov_b32_e32 v121, v106
	v_lshl_add_u64 v[202:203], v[120:121], 1, s[10:11]
	v_lshl_add_u64 v[202:203], v[0:1], 1, v[202:203]
	v_add_co_u32_e32 v204, vcc, 0x1000, v202
	s_nop 1
	v_addc_co_u32_e32 v205, vcc, 0, v203, vcc
	global_load_dwordx4 v[78:81], v[202:203], off
	s_nop 0
	global_load_dwordx4 v[94:97], v[204:205], off offset:1408
; DI unsigned cvtpk(float lo, float hi) { f32x2 v = {lo, hi}; bfv2 r = __builtin_convertvector(v, bfv2); return __builtin_bit_cast(unsigned, r); }
; DI float bflo(unsigned w) { return __uint_as_float(w << 16); }
; DI float bfhi(unsigned w) { return __uint_as_float(w & 0xffff0000u); }
; DI float silu_f(float v) { return v * __builtin_amdgcn_rcpf(1.f + __expf(-v)); }
; DI void seq_of(int m, int& base, int& t, int& T) { if (m < MP) { base = m & ~2047; t = m & 2047; T = 2048; } else { int r = m - MP; base = MP + (r & ~16383); t = r & 16383; T = 16384; } }
; DI void phase_ffn_act(const Params& p, int slab) {
;     ...
;     for (int ml = t_beg; ml < t_end; ++ml) {
;         ldrow(ml + 4, gn4, un4);
;         int base, t, T; seq_of(m0 + ml, base, t, T);
;         const float mp = t > 0 ? 1.f : 0.f, mn = t + 1 < T ? 1.f : 0.f;
;         const unsigned gpa[4] = {gp.x, gp.y, gp.z, gp.w}, gca[4] = {gc.x, gc.y, gc.z, gc.w}, gna[4] = {gn.x, gn.y, gn.z, gn.w};
;         const unsigned upa[4] = {up.x, up.y, up.z, up.w}, uca[4] = {uc.x, uc.y, uc.z, uc.w}, una[4] = {un.x, un.y, un.z, un.w};
;         float r[8];
; #pragma unroll
;         for (int e = 0; e < 4; ++e) {
;             const float g0 = bg[2 * e] + mp * bflo(gpa[e]) * wg[0][2 * e] + bflo(gca[e]) * wg[1][2 * e] + mn * bflo(gna[e]) * wg[2][2 * e];
;             const float g1 = bg[2 * e + 1] + mp * bfhi(gpa[e]) * wg[0][2 * e + 1] + bfhi(gca[e]) * wg[1][2 * e + 1] + mn * bfhi(gna[e]) * wg[2][2 * e + 1];
;             const float u0 = bu[2 * e] + mp * bflo(upa[e]) * wu[0][2 * e] + bflo(uca[e]) * wu[1][2 * e] + mn * bflo(una[e]) * wu[2][2 * e];
;             const float u1 = bu[2 * e + 1] + mp * bfhi(upa[e]) * wu[0][2 * e + 1] + bfhi(uca[e]) * wu[1][2 * e + 1] + mn * bfhi(una[e]) * wu[2][2 * e + 1];
;             r[2 * e] = silu_f(g0) * u0; r[2 * e + 1] = silu_f(g1) * u1;
;         }
;         *(u32x4*)(act + (size_t)ml * DFFP + c8) = (u32x4){cvtpk(r[0], r[1]), cvtpk(r[2], r[3]), cvtpk(r[4], r[5]), cvtpk(r[6], r[7])};
;         gp = gc; up = uc; gc = gn; uc = un; gn = gn2; un = un2; gn2 = gn3; un2 = un3; gn3 = gn4; un3 = un4;
;     }
.Lffab_e_body:
	s_or_b64 exec, exec, s[18:19]
	v_cmp_gt_i32_e32 vcc, s21, v122
	v_lshlrev_b32_e32 v130, 16, v82
	v_and_b32_e32 v131, 0xffff0000, v82
	v_cndmask_b32_e32 v107, v124, v125, vcc
	v_and_b32_e32 v107, v107, v122
	v_cndmask_b32_e32 v109, v126, v127, vcc
	v_cmp_eq_u32_e32 vcc, 0, v107
	v_add_u32_e32 v107, 1, v107
	v_lshlrev_b32_e32 v132, 16, v66
	v_cndmask_b32_e64 v108, 1.0, 0, vcc
	v_pk_mul_f32 v[130:131], v[108:109], v[130:131] op_sel_hi:[0,1]
	v_cmp_lt_u32_e32 vcc, v107, v109
	v_pk_fma_f32 v[130:131], v[22:23], v[130:131], v[6:7]
	v_and_b32_e32 v133, 0xffff0000, v66
	v_cndmask_b32_e64 v128, 0, 1.0, vcc
	v_pk_fma_f32 v[130:131], v[30:31], v[132:133], v[130:131]
	v_lshlrev_b32_e32 v132, 16, v86
	v_and_b32_e32 v133, 0xffff0000, v86
	v_pk_mul_f32 v[132:133], v[128:129], v[132:133] op_sel_hi:[0,1]
	v_pk_fma_f32 v[130:131], v[46:47], v[132:133], v[130:131]
	v_lshlrev_b32_e32 v132, 16, v74
	v_and_b32_e32 v133, 0xffff0000, v74
	v_mul_f32_e32 v74, 0xbfb8aa3b, v130
	v_exp_f32_e32 v74, v74
	v_mul_f32_e32 v82, 0xbfb8aa3b, v131
	v_exp_f32_e32 v82, v82
	v_pk_mul_f32 v[132:133], v[108:109], v[132:133] op_sel_hi:[0,1]
	v_add_f32_e32 v74, 1.0, v74
	v_rcp_f32_e32 v136, v74
	v_add_f32_e32 v74, 1.0, v82
	v_rcp_f32_e32 v137, v74
	v_pk_fma_f32 v[132:133], v[26:27], v[132:133], v[10:11]
	v_lshlrev_b32_e32 v134, 16, v70
	v_and_b32_e32 v135, 0xffff0000, v70
	v_pk_fma_f32 v[132:133], v[42:43], v[134:135], v[132:133]
	v_lshlrev_b32_e32 v134, 16, v90
	v_and_b32_e32 v135, 0xffff0000, v90
	v_pk_mul_f32 v[134:135], v[128:129], v[134:135] op_sel_hi:[0,1]
	v_lshlrev_b32_e32 v82, 16, v83
	v_and_b32_e32 v83, 0xffff0000, v83
	v_pk_fma_f32 v[132:133], v[58:59], v[134:135], v[132:133]
	v_pk_mul_f32 v[130:131], v[130:131], v[136:137]
	v_pk_mul_f32 v[82:83], v[108:109], v[82:83] op_sel_hi:[0,1]
	v_pk_mul_f32 v[130:131], v[132:133], v[130:131]
	v_pk_fma_f32 v[82:83], v[24:25], v[82:83], v[8:9]
	v_lshlrev_b32_e32 v132, 16, v67
	v_and_b32_e32 v133, 0xffff0000, v67
	v_pk_fma_f32 v[82:83], v[32:33], v[132:133], v[82:83]
	v_lshlrev_b32_e32 v132, 16, v87
	v_and_b32_e32 v133, 0xffff0000, v87
	v_pk_mul_f32 v[132:133], v[128:129], v[132:133] op_sel_hi:[0,1]
	v_pk_fma_f32 v[82:83], v[48:49], v[132:133], v[82:83]
	v_lshlrev_b32_e32 v74, 16, v75
	v_and_b32_e32 v75, 0xffff0000, v75
	v_mul_f32_e32 v107, 0xbfb8aa3b, v82
	v_pk_mul_f32 v[74:75], v[108:109], v[74:75] op_sel_hi:[0,1]
	v_exp_f32_e32 v107, v107
	v_mul_f32_e32 v109, 0xbfb8aa3b, v83
	v_exp_f32_e32 v109, v109
	v_pk_fma_f32 v[74:75], v[28:29], v[74:75], v[12:13]
	v_add_f32_e32 v107, 1.0, v107
	v_rcp_f32_e32 v134, v107
	v_add_f32_e32 v107, 1.0, v109
	v_rcp_f32_e32 v135, v107
	v_lshlrev_b32_e32 v132, 16, v71
	v_and_b32_e32 v133, 0xffff0000, v71
	v_pk_fma_f32 v[74:75], v[44:45], v[132:133], v[74:75]
	v_lshlrev_b32_e32 v132, 16, v91
	v_and_b32_e32 v133, 0xffff0000, v91
	v_pk_mul_f32 v[132:133], v[128:129], v[132:133] op_sel_hi:[0,1]
	v_pk_fma_f32 v[74:75], v[60:61], v[132:133], v[74:75]
	v_pk_mul_f32 v[82:83], v[82:83], v[134:135]
	v_lshlrev_b32_e32 v132, 16, v68
	v_pk_mul_f32 v[82:83], v[74:75], v[82:83]
	v_lshlrev_b32_e32 v74, 16, v84
	v_and_b32_e32 v75, 0xffff0000, v84
	v_pk_mul_f32 v[74:75], v[108:109], v[74:75] op_sel_hi:[0,1]
	v_pk_fma_f32 v[74:75], v[18:19], v[74:75], v[2:3]
	v_and_b32_e32 v133, 0xffff0000, v68
	v_pk_fma_f32 v[74:75], v[38:39], v[132:133], v[74:75]
	v_lshlrev_b32_e32 v132, 16, v88
	v_and_b32_e32 v133, 0xffff0000, v88
	v_pk_mul_f32 v[132:133], v[128:129], v[132:133] op_sel_hi:[0,1]
	v_pk_fma_f32 v[74:75], v[54:55], v[132:133], v[74:75]
	v_lshlrev_b32_e32 v132, 16, v76
	v_and_b32_e32 v133, 0xffff0000, v76
	v_mul_f32_e32 v76, 0xbfb8aa3b, v74
	v_exp_f32_e32 v76, v76
	v_mul_f32_e32 v84, 0xbfb8aa3b, v75
	v_exp_f32_e32 v84, v84
	v_pk_mul_f32 v[132:133], v[108:109], v[132:133] op_sel_hi:[0,1]
	v_add_f32_e32 v76, 1.0, v76
	v_rcp_f32_e32 v136, v76
	v_add_f32_e32 v76, 1.0, v84
	v_rcp_f32_e32 v137, v76
	v_pk_fma_f32 v[132:133], v[34:35], v[132:133], v[14:15]
	v_lshlrev_b32_e32 v134, 16, v72
	v_and_b32_e32 v135, 0xffff0000, v72
	v_pk_fma_f32 v[132:133], v[50:51], v[134:135], v[132:133]
	v_lshlrev_b32_e32 v134, 16, v92
	v_and_b32_e32 v135, 0xffff0000, v92
	v_pk_mul_f32 v[134:135], v[128:129], v[134:135] op_sel_hi:[0,1]
	v_pk_fma_f32 v[132:133], v[62:63], v[134:135], v[132:133]
	v_pk_mul_f32 v[74:75], v[74:75], v[136:137]
	v_lshlrev_b32_e32 v84, 16, v69
	v_pk_mul_f32 v[132:133], v[132:133], v[74:75]
	v_lshlrev_b32_e32 v74, 16, v85
	v_and_b32_e32 v75, 0xffff0000, v85
	v_pk_mul_f32 v[74:75], v[108:109], v[74:75] op_sel_hi:[0,1]
	v_pk_fma_f32 v[74:75], v[20:21], v[74:75], v[4:5]
	v_and_b32_e32 v85, 0xffff0000, v69
	v_pk_fma_f32 v[74:75], v[40:41], v[84:85], v[74:75]
	v_lshlrev_b32_e32 v84, 16, v89
	v_and_b32_e32 v85, 0xffff0000, v89
	v_lshlrev_b32_e32 v76, 16, v77
	v_and_b32_e32 v77, 0xffff0000, v77
	v_pk_mul_f32 v[84:85], v[128:129], v[84:85] op_sel_hi:[0,1]
	v_pk_mul_f32 v[76:77], v[108:109], v[76:77] op_sel_hi:[0,1]
	v_pk_fma_f32 v[74:75], v[56:57], v[84:85], v[74:75]
	v_pk_fma_f32 v[76:77], v[36:37], v[76:77], v[16:17]
	v_lshlrev_b32_e32 v84, 16, v73
	v_and_b32_e32 v85, 0xffff0000, v73
	v_pk_fma_f32 v[76:77], v[52:53], v[84:85], v[76:77]
	v_mul_f32_e32 v84, 0xbfb8aa3b, v74
	v_exp_f32_e32 v85, v84
	v_mul_f32_e32 v84, 0xbfb8aa3b, v75
	v_exp_f32_e32 v107, v84
	v_lshlrev_b32_e32 v84, 16, v93
	v_add_f32_e32 v85, 1.0, v85
	v_rcp_f32_e32 v108, v85
	v_add_f32_e32 v85, 1.0, v107
	v_rcp_f32_e32 v109, v85
	v_and_b32_e32 v85, 0xffff0000, v93
	v_pk_mul_f32 v[84:85], v[128:129], v[84:85] op_sel_hi:[0,1]
	v_pk_fma_f32 v[76:77], v[64:65], v[84:85], v[76:77]
	v_pk_mul_f32 v[74:75], v[74:75], v[108:109]
	v_add_u32_e32 v122, 1, v122
	v_pk_mul_f32 v[84:85], v[76:77], v[74:75]
	v_cvt_pk_bf16_f32 v74, v130, v131
	v_cvt_pk_bf16_f32 v75, v82, v83
	v_cvt_pk_bf16_f32 v76, v132, v133
	v_cvt_pk_bf16_f32 v77, v84, v85
	global_store_dwordx4 v[118:119], v[74:77], off
	v_mov_b64_e32 v[84:85], v[68:69]
	v_mov_b64_e32 v[82:83], v[66:67]
	v_mov_b64_e32 v[76:77], v[72:73]
	v_mov_b64_e32 v[74:75], v[70:71]
	v_mov_b64_e32 v[66:67], v[86:87]
	v_mov_b64_e32 v[70:71], v[90:91]
	v_cmp_ge_i32_e32 vcc, v122, v123
	v_mov_b64_e32 v[68:69], v[88:89]
	v_mov_b64_e32 v[72:73], v[92:93]
	v_mov_b64_e32 v[90:91], v[114:115]
	v_mov_b64_e32 v[86:87], v[110:111]
	v_lshl_add_u64 v[118:119], v[118:119], 0, s[16:17]
	v_add_u32_e32 v120, 0x1580, v120
	s_or_b64 s[14:15], vcc, s[14:15]
	v_mov_b64_e32 v[92:93], v[116:117]
	v_mov_b64_e32 v[88:89], v[112:113]
	s_andn2_b64 exec, exec, s[14:15]
	s_cbranch_execz .LBB0_905
	s_cmp_eq_u32 s24, 0
	s_cbranch_scc1 .Lffab_o_st
	s_waitcnt vmcnt(0)
	s_branch .Lffab_o_go

; DI void phase_ffn_act(const Params& p, int slab) {
;     ...
;     auto ldrow = [&](int ml, u32x4& g, u32x4& u) {
;         if (ml >= 0 && ml < MSLAB) { const bf16_t* row = us + (size_t)ml * DFF2; g = *(const u32x4*)(row + c8); u = *(const u32x4*)(row + DFF + c8); }
;         else { g = (u32x4){0u, 0u, 0u, 0u}; u = g; }
;     };
;     u32x4 gp, up, gc, uc, gn, un, gn2, un2, gn3, un3, gn4, un4;
;     ldrow(t_beg - 1, gp, up); ldrow(t_beg, gc, uc); ldrow(t_beg + 1, gn, un); ldrow(t_beg + 2, gn2, un2); ldrow(t_beg + 3, gn3, un3);
;     for (int ml = t_beg; ml < t_end; ++ml) {
;         ldrow(ml + 4, gn4, un4);
.Lffab_o_go:
	v_mov_b64_e32 v[110:111], v[98:99]
	v_mov_b64_e32 v[112:113], v[100:101]
	v_mov_b64_e32 v[114:115], v[102:103]
	v_mov_b64_e32 v[116:117], v[104:105]
	v_add_u32_e32 v201, 4, v122
	v_mov_b32_e32 v107, v106
	v_cmp_gt_u32_e32 vcc, s20, v201
	v_mov_b32_e32 v108, v106
	v_mov_b32_e32 v109, v106
	v_mov_b64_e32 v[98:99], v[106:107]
	v_mov_b64_e32 v[102:103], v[106:107]
	v_mov_b64_e32 v[100:101], v[108:109]
	v_mov_b64_e32 v[104:105], v[108:109]
	s_and_saveexec_b64 s[18:19], vcc
	s_cbranch_execz .Lffab_o_skip
	v_mov_b32_e32 v121, v106
	v_lshl_add_u64 v[202:203], v[120:121], 1, s[10:11]
	v_lshl_add_u64 v[202:203], v[0:1], 1, v[202:203]
	v_add_co_u32_e32 v204, vcc, 0x1000, v202
	s_nop 1
	v_addc_co_u32_e32 v205, vcc, 0, v203, vcc
	global_load_dwordx4 v[98:101], v[202:203], off
	s_nop 0
	global_load_dwordx4 v[102:105], v[204:205], off offset:1408
; DI unsigned cvtpk(float lo, float hi) { f32x2 v = {lo, hi}; bfv2 r = __builtin_convertvector(v, bfv2); return __builtin_bit_cast(unsigned, r); }
; DI float bflo(unsigned w) { return __uint_as_float(w << 16); }
; DI float bfhi(unsigned w) { return __uint_as_float(w & 0xffff0000u); }
; DI float silu_f(float v) { return v * __builtin_amdgcn_rcpf(1.f + __expf(-v)); }
; DI void seq_of(int m, int& base, int& t, int& T) { if (m < MP) { base = m & ~2047; t = m & 2047; T = 2048; } else { int r = m - MP; base = MP + (r & ~16383); t = r & 16383; T = 16384; } }
; DI void phase_ffn_act(const Params& p, int slab) {
;     ...
;     for (int ml = t_beg; ml < t_end; ++ml) {
;         ldrow(ml + 4, gn4, un4);
;         int base, t, T; seq_of(m0 + ml, base, t, T);
;         const float mp = t > 0 ? 1.f : 0.f, mn = t + 1 < T ? 1.f : 0.f;
;         const unsigned gpa[4] = {gp.x, gp.y, gp.z, gp.w}, gca[4] = {gc.x, gc.y, gc.z, gc.w}, gna[4] = {gn.x, gn.y, gn.z, gn.w};
;         const unsigned upa[4] = {up.x, up.y, up.z, up.w}, uca[4] = {uc.x, uc.y, uc.z, uc.w}, una[4] = {un.x, un.y, un.z, un.w};
;         float r[8];
; #pragma unroll
;         for (int e = 0; e < 4; ++e) {
;             const float g0 = bg[2 * e] + mp * bflo(gpa[e]) * wg[0][2 * e] + bflo(gca[e]) * wg[1][2 * e] + mn * bflo(gna[e]) * wg[2][2 * e];
;             const float g1 = bg[2 * e + 1] + mp * bfhi(gpa[e]) * wg[0][2 * e + 1] + bfhi(gca[e]) * wg[1][2 * e + 1] + mn * bfhi(gna[e]) * wg[2][2 * e + 1];
;             const float u0 = bu[2 * e] + mp * bflo(upa[e]) * wu[0][2 * e] + bflo(uca[e]) * wu[1][2 * e] + mn * bflo(una[e]) * wu[2][2 * e];
;             const float u1 = bu[2 * e + 1] + mp * bfhi(upa[e]) * wu[0][2 * e + 1] + bfhi(uca[e]) * wu[1][2 * e + 1] + mn * bfhi(una[e]) * wu[2][2 * e + 1];
;             r[2 * e] = silu_f(g0) * u0; r[2 * e + 1] = silu_f(g1) * u1;
;         }
;         *(u32x4*)(act + (size_t)ml * DFFP + c8) = (u32x4){cvtpk(r[0], r[1]), cvtpk(r[2], r[3]), cvtpk(r[4], r[5]), cvtpk(r[6], r[7])};
;         gp = gc; up = uc; gc = gn; uc = un; gn = gn2; un = un2; gn2 = gn3; un2 = un3; gn3 = gn4; un3 = un4;
;     }
.Lffab_o_body:
	s_or_b64 exec, exec, s[18:19]
	v_cmp_gt_i32_e32 vcc, s21, v122
	v_lshlrev_b32_e32 v130, 16, v82
	v_and_b32_e32 v131, 0xffff0000, v82
	v_cndmask_b32_e32 v107, v124, v125, vcc
	v_and_b32_e32 v107, v107, v122
	v_cndmask_b32_e32 v109, v126, v127, vcc
	v_cmp_eq_u32_e32 vcc, 0, v107
	v_add_u32_e32 v107, 1, v107
	v_lshlrev_b32_e32 v132, 16, v66
	v_cndmask_b32_e64 v108, 1.0, 0, vcc
	v_pk_mul_f32 v[130:131], v[108:109], v[130:131] op_sel_hi:[0,1]
	v_cmp_lt_u32_e32 vcc, v107, v109
	v_pk_fma_f32 v[130:131], v[22:23], v[130:131], v[6:7]
	v_and_b32_e32 v133, 0xffff0000, v66
	v_cndmask_b32_e64 v128, 0, 1.0, vcc
	v_pk_fma_f32 v[130:131], v[30:31], v[132:133], v[130:131]
	v_lshlrev_b32_e32 v132, 16, v86
	v_and_b32_e32 v133, 0xffff0000, v86
	v_pk_mul_f32 v[132:133], v[128:129], v[132:133] op_sel_hi:[0,1]
	v_pk_fma_f32 v[130:131], v[46:47], v[132:133], v[130:131]
	v_lshlrev_b32_e32 v132, 16, v74
	v_and_b32_e32 v133, 0xffff0000, v74
	v_mul_f32_e32 v74, 0xbfb8aa3b, v130
	v_exp_f32_e32 v74, v74
	v_mul_f32_e32 v82, 0xbfb8aa3b, v131
	v_exp_f32_e32 v82, v82
	v_pk_mul_f32 v[132:133], v[108:109], v[132:133] op_sel_hi:[0,1]
	v_add_f32_e32 v74, 1.0, v74
	v_rcp_f32_e32 v136, v74
	v_add_f32_e32 v74, 1.0, v82
	v_rcp_f32_e32 v137, v74
	v_pk_fma_f32 v[132:133], v[26:27], v[132:133], v[10:11]
	v_lshlrev_b32_e32 v134, 16, v70
	v_and_b32_e32 v135, 0xffff0000, v70
	v_pk_fma_f32 v[132:133], v[42:43], v[134:135], v[132:133]
	v_lshlrev_b32_e32 v134, 16, v90
	v_and_b32_e32 v135, 0xffff0000, v90
	v_pk_mul_f32 v[134:135], v[128:129], v[134:135] op_sel_hi:[0,1]
	v_lshlrev_b32_e32 v82, 16, v83
	v_and_b32_e32 v83, 0xffff0000, v83
	v_pk_fma_f32 v[132:133], v[58:59], v[134:135], v[132:133]
	v_pk_mul_f32 v[130:131], v[130:131], v[136:137]
	v_pk_mul_f32 v[82:83], v[108:109], v[82:83] op_sel_hi:[0,1]
	v_pk_mul_f32 v[130:131], v[132:133], v[130:131]
	v_pk_fma_f32 v[82:83], v[24:25], v[82:83], v[8:9]
	v_lshlrev_b32_e32 v132, 16, v67
	v_and_b32_e32 v133, 0xffff0000, v67
	v_pk_fma_f32 v[82:83], v[32:33], v[132:133], v[82:83]
	v_lshlrev_b32_e32 v132, 16, v87
	v_and_b32_e32 v133, 0xffff0000, v87
	v_pk_mul_f32 v[132:133], v[128:129], v[132:133] op_sel_hi:[0,1]
	v_pk_fma_f32 v[82:83], v[48:49], v[132:133], v[82:83]
	v_lshlrev_b32_e32 v74, 16, v75
	v_and_b32_e32 v75, 0xffff0000, v75
	v_mul_f32_e32 v107, 0xbfb8aa3b, v82
	v_pk_mul_f32 v[74:75], v[108:109], v[74:75] op_sel_hi:[0,1]
	v_exp_f32_e32 v107, v107
	v_mul_f32_e32 v109, 0xbfb8aa3b, v83
	v_exp_f32_e32 v109, v109
	v_pk_fma_f32 v[74:75], v[28:29], v[74:75], v[12:13]
	v_add_f32_e32 v107, 1.0, v107
	v_rcp_f32_e32 v134, v107
	v_add_f32_e32 v107, 1.0, v109
	v_rcp_f32_e32 v135, v107
	v_lshlrev_b32_e32 v132, 16, v71
	v_and_b32_e32 v133, 0xffff0000, v71
	v_pk_fma_f32 v[74:75], v[44:45], v[132:133], v[74:75]
	v_lshlrev_b32_e32 v132, 16, v91
	v_and_b32_e32 v133, 0xffff0000, v91
	v_pk_mul_f32 v[132:133], v[128:129], v[132:133] op_sel_hi:[0,1]
	v_pk_fma_f32 v[74:75], v[60:61], v[132:133], v[74:75]
	v_pk_mul_f32 v[82:83], v[82:83], v[134:135]
	v_lshlrev_b32_e32 v132, 16, v68
	v_pk_mul_f32 v[82:83], v[74:75], v[82:83]
	v_lshlrev_b32_e32 v74, 16, v84
	v_and_b32_e32 v75, 0xffff0000, v84
	v_pk_mul_f32 v[74:75], v[108:109], v[74:75] op_sel_hi:[0,1]
	v_pk_fma_f32 v[74:75], v[18:19], v[74:75], v[2:3]
	v_and_b32_e32 v133, 0xffff0000, v68
	v_pk_fma_f32 v[74:75], v[38:39], v[132:133], v[74:75]
	v_lshlrev_b32_e32 v132, 16, v88
	v_and_b32_e32 v133, 0xffff0000, v88
	v_pk_mul_f32 v[132:133], v[128:129], v[132:133] op_sel_hi:[0,1]
	v_pk_fma_f32 v[74:75], v[54:55], v[132:133], v[74:75]
	v_lshlrev_b32_e32 v132, 16, v76
	v_and_b32_e32 v133, 0xffff0000, v76
	v_mul_f32_e32 v76, 0xbfb8aa3b, v74
	v_exp_f32_e32 v76, v76
	v_mul_f32_e32 v84, 0xbfb8aa3b, v75
	v_exp_f32_e32 v84, v84
	v_pk_mul_f32 v[132:133], v[108:109], v[132:133] op_sel_hi:[0,1]
	v_add_f32_e32 v76, 1.0, v76
	v_rcp_f32_e32 v136, v76
	v_add_f32_e32 v76, 1.0, v84
	v_rcp_f32_e32 v137, v76
	v_pk_fma_f32 v[132:133], v[34:35], v[132:133], v[14:15]
	v_lshlrev_b32_e32 v134, 16, v72
	v_and_b32_e32 v135, 0xffff0000, v72
	v_pk_fma_f32 v[132:133], v[50:51], v[134:135], v[132:133]
	v_lshlrev_b32_e32 v134, 16, v92
	v_and_b32_e32 v135, 0xffff0000, v92
	v_pk_mul_f32 v[134:135], v[128:129], v[134:135] op_sel_hi:[0,1]
	v_pk_fma_f32 v[132:133], v[62:63], v[134:135], v[132:133]
	v_pk_mul_f32 v[74:75], v[74:75], v[136:137]
	v_lshlrev_b32_e32 v84, 16, v69
	v_pk_mul_f32 v[132:133], v[132:133], v[74:75]
	v_lshlrev_b32_e32 v74, 16, v85
	v_and_b32_e32 v75, 0xffff0000, v85
	v_pk_mul_f32 v[74:75], v[108:109], v[74:75] op_sel_hi:[0,1]
	v_pk_fma_f32 v[74:75], v[20:21], v[74:75], v[4:5]
	v_and_b32_e32 v85, 0xffff0000, v69
	v_pk_fma_f32 v[74:75], v[40:41], v[84:85], v[74:75]
	v_lshlrev_b32_e32 v84, 16, v89
	v_and_b32_e32 v85, 0xffff0000, v89
	v_lshlrev_b32_e32 v76, 16, v77
	v_and_b32_e32 v77, 0xffff0000, v77
	v_pk_mul_f32 v[84:85], v[128:129], v[84:85] op_sel_hi:[0,1]
	v_pk_mul_f32 v[76:77], v[108:109], v[76:77] op_sel_hi:[0,1]
	v_pk_fma_f32 v[74:75], v[56:57], v[84:85], v[74:75]
	v_pk_fma_f32 v[76:77], v[36:37], v[76:77], v[16:17]
	v_lshlrev_b32_e32 v84, 16, v73
	v_and_b32_e32 v85, 0xffff0000, v73
	v_pk_fma_f32 v[76:77], v[52:53], v[84:85], v[76:77]
	v_mul_f32_e32 v84, 0xbfb8aa3b, v74
	v_exp_f32_e32 v85, v84
	v_mul_f32_e32 v84, 0xbfb8aa3b, v75
	v_exp_f32_e32 v107, v84
	v_lshlrev_b32_e32 v84, 16, v93
	v_add_f32_e32 v85, 1.0, v85
	v_rcp_f32_e32 v108, v85
	v_add_f32_e32 v85, 1.0, v107
	v_rcp_f32_e32 v109, v85
	v_and_b32_e32 v85, 0xffff0000, v93
	v_pk_mul_f32 v[84:85], v[128:129], v[84:85] op_sel_hi:[0,1]
	v_pk_fma_f32 v[76:77], v[64:65], v[84:85], v[76:77]
	v_pk_mul_f32 v[74:75], v[74:75], v[108:109]
	v_add_u32_e32 v122, 1, v122
	v_pk_mul_f32 v[84:85], v[76:77], v[74:75]
	v_cvt_pk_bf16_f32 v74, v130, v131
	v_cvt_pk_bf16_f32 v75, v82, v83
	v_cvt_pk_bf16_f32 v76, v132, v133
	v_cvt_pk_bf16_f32 v77, v84, v85
	global_store_dwordx4 v[118:119], v[74:77], off
	v_mov_b64_e32 v[84:85], v[68:69]
	v_mov_b64_e32 v[82:83], v[66:67]
	v_mov_b64_e32 v[76:77], v[72:73]
	v_mov_b64_e32 v[74:75], v[70:71]
	v_mov_b64_e32 v[66:67], v[86:87]
	v_mov_b64_e32 v[70:71], v[90:91]
	v_cmp_ge_i32_e32 vcc, v122, v123
	v_mov_b64_e32 v[68:69], v[88:89]
	v_mov_b64_e32 v[72:73], v[92:93]
	v_mov_b64_e32 v[90:91], v[114:115]
	v_mov_b64_e32 v[86:87], v[110:111]
	v_lshl_add_u64 v[118:119], v[118:119], 0, s[16:17]
	v_add_u32_e32 v120, 0x1580, v120
	s_or_b64 s[14:15], vcc, s[14:15]
	v_mov_b64_e32 v[92:93], v[116:117]
	v_mov_b64_e32 v[88:89], v[112:113]
	s_andn2_b64 exec, exec, s[14:15]
	s_cbranch_execz .LBB0_905
	s_branch .LBB0_903
